# M2 EpiResid epilogue: 8 y loads per 32-row group hoisted to group start, counted vmcnt(7) instead of vmcnt(0)
# baseline (speedup 1.0000x reference)
.LBB0_1370:
	s_mul_hi_i32 s2, s7, 0x2aaaaaab
	s_lshr_b32 s3, s2, 31
	s_ashr_i32 s2, s2, 3
	s_add_i32 s2, s2, s3
	s_mul_i32 s3, s2, 48
	v_mov_b32_e32 v130, v155
	s_sub_i32 s8, s7, s3
	s_lshl_b32 s2, s2, 8
	s_nop 0
	v_cmp_lt_i32_e32 vcc, s39, v130
	s_barrier
	s_and_saveexec_b64 s[4:5], vcc
	s_xor_b64 s[4:5], exec, s[4:5]
	s_cbranch_execz .LBB0_1372
	s_lshl_b32 s3, s8, 10
	s_and_b32 s3, s3, 0xfffff000
	s_addk_i32 s3, 0xd000
	s_cmp_gt_i32 s8, 15
	s_cselect_b32 s72, s3, 0
	s_lshl_b64 s[10:11], s[72:73], 2
	s_add_u32 s9, s1, s10
	s_addc_u32 s12, s6, s11
	s_ashr_i32 s3, s2, 31
	s_lshl_b64 s[10:11], s[2:3], 2
	s_add_u32 s10, s9, s10
	s_addc_u32 s11, s12, s11
	v_mov_b32_e32 v131, v129
	v_lshl_add_u64 v[0:1], v[130:131], 2, s[10:11]
	v_add_co_u32_e32 v0, vcc, 0x147000, v0
	s_nop 1
	v_addc_co_u32_e32 v1, vcc, 0, v1, vcc
	global_load_dword v0, v[0:1], off offset:3072
.LBB0_1372:
	s_or_saveexec_b64 s[4:5], s[4:5]
	s_lshl_b32 s3, s8, 8
	s_xor_b64 exec, exec, s[4:5]
	s_cbranch_execz .LBB0_1374
	s_waitcnt vmcnt(0)
	v_add_u32_e32 v0, s3, v130
	v_ashrrev_i32_e32 v1, 31, v0
	v_lshl_add_u64 v[0:1], v[0:1], 2, s[44:45]
	v_add_co_u32_e32 v2, vcc, 0xc000, v0
	global_load_dword v4, v[0:1], off
	s_nop 0
	v_addc_co_u32_e32 v3, vcc, 0, v1, vcc
	global_load_dword v5, v[2:3], off
	v_add_co_u32_e32 v2, vcc, 0x18000, v0
	s_mov_b32 s8, 0x800000
	s_nop 0
	v_addc_co_u32_e32 v3, vcc, 0, v1, vcc
	global_load_dword v6, v[2:3], off
	v_add_co_u32_e32 v2, vcc, 0x24000, v0
	s_nop 1
	v_addc_co_u32_e32 v3, vcc, 0, v1, vcc
	global_load_dword v7, v[2:3], off
	v_add_co_u32_e32 v2, vcc, 0x30000, v0
	s_nop 1
	v_addc_co_u32_e32 v3, vcc, 0, v1, vcc
	global_load_dword v8, v[2:3], off
	v_add_co_u32_e32 v2, vcc, 0x3c000, v0
	s_nop 1
	v_addc_co_u32_e32 v3, vcc, 0, v1, vcc
	global_load_dword v9, v[2:3], off
	v_add_co_u32_e32 v2, vcc, 0x48000, v0
	s_nop 1
	v_addc_co_u32_e32 v3, vcc, 0, v1, vcc
	global_load_dword v10, v[2:3], off
	v_add_co_u32_e32 v2, vcc, 0x54000, v0
	s_nop 1
	v_addc_co_u32_e32 v3, vcc, 0, v1, vcc
	global_load_dword v11, v[2:3], off
	v_add_co_u32_e32 v2, vcc, 0x60000, v0
	s_nop 1
	v_addc_co_u32_e32 v3, vcc, 0, v1, vcc
	global_load_dword v12, v[2:3], off
	v_add_co_u32_e32 v2, vcc, 0x6c000, v0
	s_nop 1
	v_addc_co_u32_e32 v3, vcc, 0, v1, vcc
	global_load_dword v13, v[2:3], off
	v_add_co_u32_e32 v2, vcc, 0x78000, v0
	s_nop 1
	v_addc_co_u32_e32 v3, vcc, 0, v1, vcc
	global_load_dword v14, v[2:3], off
	v_add_co_u32_e32 v2, vcc, 0x84000, v0
	s_nop 1
	v_addc_co_u32_e32 v3, vcc, 0, v1, vcc
	global_load_dword v15, v[2:3], off
	v_add_co_u32_e32 v2, vcc, 0x90000, v0
	s_nop 1
	v_addc_co_u32_e32 v3, vcc, 0, v1, vcc
	global_load_dword v16, v[2:3], off
	v_add_co_u32_e32 v2, vcc, 0x9c000, v0
	s_nop 1
	v_addc_co_u32_e32 v3, vcc, 0, v1, vcc
	global_load_dword v17, v[2:3], off
	v_add_co_u32_e32 v2, vcc, 0xa8000, v0
	s_nop 1
	v_addc_co_u32_e32 v3, vcc, 0, v1, vcc
	v_add_co_u32_e32 v0, vcc, 0xb4000, v0
	global_load_dword v2, v[2:3], off
	s_nop 0
	v_addc_co_u32_e32 v1, vcc, 0, v1, vcc
	global_load_dword v0, v[0:1], off
	s_waitcnt vmcnt(15)
	v_add_f32_e32 v1, 0, v4
	s_waitcnt vmcnt(14)
	v_add_f32_e32 v1, v1, v5
	s_waitcnt vmcnt(13)
	v_add_f32_e32 v1, v1, v6
	s_waitcnt vmcnt(12)
	v_add_f32_e32 v1, v1, v7
	s_waitcnt vmcnt(11)
	v_add_f32_e32 v1, v1, v8
	s_waitcnt vmcnt(10)
	v_add_f32_e32 v1, v1, v9
	s_waitcnt vmcnt(9)
	v_add_f32_e32 v1, v1, v10
	s_waitcnt vmcnt(8)
	v_add_f32_e32 v1, v1, v11
	s_waitcnt vmcnt(7)
	v_add_f32_e32 v1, v1, v12
	s_waitcnt vmcnt(6)
	v_add_f32_e32 v1, v1, v13
	s_waitcnt vmcnt(5)
	v_add_f32_e32 v1, v1, v14
	s_waitcnt vmcnt(4)
	v_add_f32_e32 v1, v1, v15
	s_waitcnt vmcnt(3)
	v_add_f32_e32 v1, v1, v16
	s_waitcnt vmcnt(2)
	v_add_f32_e32 v1, v1, v17
	s_waitcnt vmcnt(1)
	v_add_f32_e32 v1, v1, v2
	s_waitcnt vmcnt(0)
	v_add_f32_e32 v0, v1, v0
	v_fmamk_f32 v0, v0, 0x3a800000, v163
	v_cmp_gt_f32_e32 vcc, s8, v0
	v_mul_f32_e32 v1, 0x4b800000, v0
	s_nop 0
	v_cndmask_b32_e32 v0, v0, v1, vcc
	v_rsq_f32_e32 v0, v0
	s_nop 0
	v_mul_f32_e32 v1, 0x45800000, v0
	v_cndmask_b32_e32 v0, v0, v1, vcc
.LBB0_1374:
	s_or_b64 exec, exec, s[4:5]
	v_ashrrev_i32_e32 v145, 6, v130
	v_lshrrev_b32_e32 v1, 31, v130
	v_add_u32_e32 v10, v145, v1
	v_lshrrev_b32_e32 v13, 4, v130
	v_and_b32_e32 v1, 0x1fffffe, v10
	v_xor_b32_e32 v6, v13, v130
	v_sub_u32_e32 v11, v145, v1
	v_ashrrev_i32_e32 v1, 3, v130
	v_lshlrev_b32_e32 v6, 4, v6
	v_add_u32_e32 v2, s3, v1
	v_and_b32_e32 v128, 0x70, v6
	v_add_u32_e32 v6, s2, v1
	v_ashrrev_i32_e32 v3, 31, v2
	v_ashrrev_i32_e32 v7, 31, v6
	v_lshlrev_b64 v[2:3], 11, v[2:3]
	v_lshlrev_b64 v[6:7], 11, v[6:7]
	v_lshl_add_u64 v[4:5], s[40:41], 0, v[2:3]
	v_lshl_add_u64 v[8:9], s[46:47], 0, v[6:7]
	v_lshl_add_u64 v[4:5], v[4:5], 0, v[128:129]
	v_lshl_add_u64 v[8:9], v[8:9], 0, v[128:129]
	v_lshlrev_b32_e32 v128, 4, v130
	v_add_u32_e32 v14, 0x2000, v128
	v_readfirstlane_b32 s4, v128
	v_lshl_add_u32 v1, v130, 2, v167
	s_mov_b32 m0, s4
	s_mov_b64 s[8:9], 0x20000
	v_readfirstlane_b32 s4, v14
	v_add_u32_e32 v14, 0x4000, v128
	s_waitcnt vmcnt(0)
	ds_write_b32 v1, v0
	global_load_lds_dwordx4 v[4:5], off
	v_lshl_add_u64 v[0:1], v[4:5], 0, s[8:9]
	s_mov_b32 m0, s4
	s_mov_b64 s[10:11], 0x40000
	v_readfirstlane_b32 s4, v14
	global_load_lds_dwordx4 v[0:1], off
	v_lshl_add_u64 v[0:1], v[4:5], 0, s[10:11]
	s_mov_b32 m0, s4
	s_mov_b64 s[12:13], 0x60000
	global_load_lds_dwordx4 v[0:1], off
	v_lshl_add_u64 v[0:1], v[4:5], 0, s[12:13]
	v_add_u32_e32 v4, 0x6000, v128
	v_bfe_u32 v12, v130, 5, 1
	v_readfirstlane_b32 s4, v4
	s_mov_b32 m0, s4
	v_add_u32_e32 v4, 0xa000, v128
	global_load_lds_dwordx4 v[0:1], off
	v_add_u32_e32 v0, 0x8000, v128
	v_and_b32_e32 v144, 31, v130
	v_readfirstlane_b32 s4, v0
	s_mov_b32 m0, s4
	v_readfirstlane_b32 s4, v4
	v_add_u32_e32 v4, 0xc000, v128
	global_load_lds_dwordx4 v[8:9], off
	v_lshl_add_u64 v[0:1], v[8:9], 0, s[8:9]
	s_mov_b32 m0, s4
	v_readfirstlane_b32 s4, v4
	v_add_u32_e32 v4, 0xe000, v128
	global_load_lds_dwordx4 v[0:1], off
	v_lshl_add_u64 v[0:1], v[8:9], 0, s[10:11]
	s_mov_b32 m0, s4
	v_readfirstlane_b32 s4, v4
	global_load_lds_dwordx4 v[0:1], off
	v_lshl_add_u64 v[0:1], v[8:9], 0, s[12:13]
	s_mov_b32 m0, s4
	v_lshlrev_b32_e32 v136, 7, v11
	global_load_lds_dwordx4 v[0:1], off
	v_lshrrev_b32_e32 v0, 1, v130
	v_bfe_u32 v1, v130, 1, 3
	v_bitop3_b32 v0, v12, v0, 7 bitop3:0x78
	v_lshlrev_b32_e32 v149, 4, v0
	v_bitop3_b32 v0, v12, v1, 2 bitop3:0x36
	v_lshlrev_b32_e32 v148, 4, v0
	v_bitop3_b32 v0, v12, v1, 4 bitop3:0x36
	v_or_b32_e32 v4, v136, v144
	v_lshlrev_b32_e32 v147, 4, v0
	v_bitop3_b32 v0, v12, v1, 6 bitop3:0x36
	v_lshlrev_b32_e32 v150, 7, v4
	v_lshlrev_b32_e32 v4, 5, v10
	v_lshlrev_b32_e32 v146, 4, v0
	v_bitop3_b32 v0, v13, 7, v130 bitop3:0x48
	v_and_b32_e32 v137, 0xffffffc0, v4
	v_lshlrev_b32_e32 v0, 4, v0
	v_or_b32_e32 v4, v137, v144
	v_or_b32_e32 v6, v6, v0
	v_or_b32_e32 v2, v2, v0
	v_mov_b32_e32 v32, 0
	v_and_b32_e32 v131, 63, v130
	v_lshlrev_b32_e32 v151, 7, v4
	v_add_u32_e32 v152, 0x8000, v150
	v_lshl_add_u64 v[132:133], s[48:49], 0, v[6:7]
	v_lshl_add_u64 v[134:135], s[14:15], 0, v[2:3]
	s_mov_b32 s8, 0
	s_mov_b64 s[4:5], 0
	v_mov_b32_e32 v33, v32
	v_mov_b32_e32 v34, v32
	v_mov_b32_e32 v35, v32
	v_mov_b32_e32 v36, v32
	v_mov_b32_e32 v37, v32
	v_mov_b32_e32 v38, v32
	v_mov_b32_e32 v39, v32
	v_mov_b32_e32 v40, v32
	v_mov_b32_e32 v41, v32
	v_mov_b32_e32 v42, v32
	v_mov_b32_e32 v43, v32
	v_mov_b32_e32 v44, v32
	v_mov_b32_e32 v45, v32
	v_mov_b32_e32 v46, v32
	v_mov_b32_e32 v47, v32
	v_mov_b32_e32 v96, v32
	v_mov_b32_e32 v97, v32
	v_mov_b32_e32 v98, v32
	v_mov_b32_e32 v99, v32
	v_mov_b32_e32 v100, v32
	v_mov_b32_e32 v101, v32
	v_mov_b32_e32 v102, v32
	v_mov_b32_e32 v103, v32
	v_mov_b32_e32 v104, v32
	v_mov_b32_e32 v105, v32
	v_mov_b32_e32 v106, v32
	v_mov_b32_e32 v107, v32
	v_mov_b32_e32 v108, v32
	v_mov_b32_e32 v109, v32
	v_mov_b32_e32 v110, v32
	v_mov_b32_e32 v111, v32
	v_mov_b32_e32 v48, v32
	v_mov_b32_e32 v49, v32
	v_mov_b32_e32 v50, v32
	v_mov_b32_e32 v51, v32
	v_mov_b32_e32 v52, v32
	v_mov_b32_e32 v53, v32
	v_mov_b32_e32 v54, v32
	v_mov_b32_e32 v55, v32
	v_mov_b32_e32 v56, v32
	v_mov_b32_e32 v57, v32
	v_mov_b32_e32 v58, v32
	v_mov_b32_e32 v59, v32
	v_mov_b32_e32 v60, v32
	v_mov_b32_e32 v61, v32
	v_mov_b32_e32 v62, v32
	v_mov_b32_e32 v63, v32
	v_mov_b32_e32 v112, v32
	v_mov_b32_e32 v113, v32
	v_mov_b32_e32 v114, v32
	v_mov_b32_e32 v115, v32
	v_mov_b32_e32 v116, v32
	v_mov_b32_e32 v117, v32
	v_mov_b32_e32 v118, v32
	v_mov_b32_e32 v119, v32
	v_mov_b32_e32 v120, v32
	v_mov_b32_e32 v121, v32
	v_mov_b32_e32 v122, v32
	v_mov_b32_e32 v123, v32
	v_mov_b32_e32 v124, v32
	v_mov_b32_e32 v125, v32
	v_mov_b32_e32 v126, v32
	v_mov_b32_e32 v127, v32
	v_mov_b32_e32 v80, v32
	v_mov_b32_e32 v81, v32
	v_mov_b32_e32 v82, v32
	v_mov_b32_e32 v83, v32
	v_mov_b32_e32 v84, v32
	v_mov_b32_e32 v85, v32
	v_mov_b32_e32 v86, v32
	v_mov_b32_e32 v87, v32
	v_mov_b32_e32 v88, v32
	v_mov_b32_e32 v89, v32
	v_mov_b32_e32 v90, v32
	v_mov_b32_e32 v91, v32
	v_mov_b32_e32 v92, v32
	v_mov_b32_e32 v93, v32
	v_mov_b32_e32 v94, v32
	v_mov_b32_e32 v95, v32
	v_mov_b32_e32 v16, v32
	v_mov_b32_e32 v17, v32
	v_mov_b32_e32 v18, v32
	v_mov_b32_e32 v19, v32
	v_mov_b32_e32 v20, v32
	v_mov_b32_e32 v21, v32
	v_mov_b32_e32 v22, v32
	v_mov_b32_e32 v23, v32
	v_mov_b32_e32 v24, v32
	v_mov_b32_e32 v25, v32
	v_mov_b32_e32 v26, v32
	v_mov_b32_e32 v27, v32
	v_mov_b32_e32 v28, v32
	v_mov_b32_e32 v29, v32
	v_mov_b32_e32 v30, v32
	v_mov_b32_e32 v31, v32
	v_mov_b32_e32 v64, v32
	v_mov_b32_e32 v65, v32
	v_mov_b32_e32 v66, v32
	v_mov_b32_e32 v67, v32
	v_mov_b32_e32 v68, v32
	v_mov_b32_e32 v69, v32
	v_mov_b32_e32 v70, v32
	v_mov_b32_e32 v71, v32
	v_mov_b32_e32 v72, v32
	v_mov_b32_e32 v73, v32
	v_mov_b32_e32 v74, v32
	v_mov_b32_e32 v75, v32
	v_mov_b32_e32 v76, v32
	v_mov_b32_e32 v77, v32
	v_mov_b32_e32 v78, v32
	v_mov_b32_e32 v79, v32
	v_mov_b32_e32 v0, v32
	v_mov_b32_e32 v1, v32
	v_mov_b32_e32 v2, v32
	v_mov_b32_e32 v3, v32
	v_mov_b32_e32 v4, v32
	v_mov_b32_e32 v5, v32
	v_mov_b32_e32 v6, v32
	v_mov_b32_e32 v7, v32
	v_mov_b32_e32 v8, v32
	v_mov_b32_e32 v9, v32
	v_mov_b32_e32 v10, v32
	v_mov_b32_e32 v11, v32
	v_mov_b32_e32 v12, v32
	v_mov_b32_e32 v13, v32
	v_mov_b32_e32 v14, v32
	v_mov_b32_e32 v15, v32
	s_mov_b64 s[12:13], 0x6ff4080

.LBB0_1434:
	s_add_i32 s9, s7, 1
	s_bitcmp1_b32 s9, 0
	s_cselect_b32 s10, 0xe000, 0
	v_add_u32_e32 v115, s10, v109
	v_lshl_add_u64 v[116:117], v[98:99], 0, s[2:3]
	s_mov_b64 s[10:11], 0x9f94080
	v_lshl_add_u64 v[118:119], v[116:117], 0, s[10:11]
	v_readfirstlane_b32 s10, v115
	s_mov_b32 m0, s10
	s_mov_b64 s[10:11], 0xa014080
	v_add_u32_e32 v120, 0x2000, v115
	s_waitcnt vmcnt(0)
	s_waitcnt vmcnt(0) lgkmcnt(0)
	s_barrier
	global_load_lds_dwordx4 v[118:119], off
	v_lshl_add_u64 v[118:119], v[116:117], 0, s[10:11]
	v_readfirstlane_b32 s10, v120
	s_mov_b32 m0, s10
	s_mov_b64 s[10:11], 0xa094080
	global_load_lds_dwordx4 v[118:119], off
	v_add_u32_e32 v118, 0x4000, v115
	v_lshl_add_u64 v[116:117], v[116:117], 0, s[10:11]
	v_readfirstlane_b32 s10, v118
	s_mov_b32 m0, s10
	s_mov_b64 s[10:11], 0x3314080
	global_load_lds_dwordx4 v[116:117], off
	v_lshl_add_u64 v[116:117], v[96:97], 0, s[2:3]
	v_add_u32_e32 v120, 0x6000, v115
	v_lshl_add_u64 v[118:119], v[116:117], 0, s[10:11]
	v_readfirstlane_b32 s10, v120
	s_mov_b32 m0, s10
	s_mov_b64 s[10:11], 0x3394080
	v_add_u32_e32 v120, 0x8000, v115
	global_load_lds_dwordx4 v[118:119], off
	v_lshl_add_u64 v[118:119], v[116:117], 0, s[10:11]
	v_readfirstlane_b32 s10, v120
	s_mov_b32 m0, s10
	s_mov_b64 s[10:11], 0x3414080
	v_add_u32_e32 v120, 0xa000, v115
	global_load_lds_dwordx4 v[118:119], off
	v_lshl_add_u64 v[118:119], v[116:117], 0, s[10:11]
	v_readfirstlane_b32 s10, v120
	s_mov_b32 m0, s10
	s_mov_b64 s[10:11], 0x3494080
	v_add_u32_e32 v115, 0xc000, v115
	v_lshl_add_u64 v[116:117], v[116:117], 0, s[10:11]
	v_readfirstlane_b32 s10, v115
	global_load_lds_dwordx4 v[118:119], off
	s_mov_b32 m0, s10
	s_nop 0
	global_load_lds_dwordx4 v[116:117], off
	s_bitcmp1_b32 s7, 0
	s_cselect_b32 s7, 0xe000, 0
	v_add_u32_e32 v115, s7, v114
	v_add_u32_e32 v120, v115, v111
	ds_read_b128 v[116:119], v120 offset:0
	v_add_u32_e32 v128, s7, v113
	ds_read_b128 v[120:123], v120 offset:0x1000
	v_add_u32_e32 v134, v128, v111
	ds_read_b128 v[124:127], v134 offset:0
	ds_read_b128 v[130:133], v134 offset:0x1000
	ds_read_b128 v[134:137], v134 offset:0x2000
	v_add_u32_e32 v148, v115, v110
	ds_read_b128 v[144:147], v148 offset:0
	ds_read_b128 v[148:151], v148 offset:0x1000
	v_add_u32_e32 v152, v128, v110
	ds_read_b128 v[182:185], v152 offset:0
	ds_read_b128 v[186:189], v152 offset:0x1000
	ds_read_b128 v[190:193], v152 offset:0x2000
	s_waitcnt lgkmcnt(5)
	s_nop 0
	v_mfma_f32_32x32x16_bf16 v[64:79], v[116:119], v[124:127], v[64:79]
	v_mfma_f32_32x32x16_bf16 v[32:47], v[116:119], v[130:133], v[32:47]
	v_mfma_f32_32x32x16_bf16 v[0:15], v[116:119], v[134:137], v[0:15]
	v_mfma_f32_32x32x16_bf16 v[80:95], v[120:123], v[124:127], v[80:95]
	v_mfma_f32_32x32x16_bf16 v[48:63], v[120:123], v[130:133], v[48:63]
	v_mfma_f32_32x32x16_bf16 v[16:31], v[120:123], v[134:137], v[16:31]
	v_add_u32_e32 v120, v115, v108
	ds_read_b128 v[116:119], v120 offset:0
	ds_read_b128 v[120:123], v120 offset:0x1000
	v_add_u32_e32 v134, v128, v108
	ds_read_b128 v[124:127], v134 offset:0
	ds_read_b128 v[130:133], v134 offset:0x1000
	ds_read_b128 v[134:137], v134 offset:0x2000
	s_waitcnt lgkmcnt(5)
	s_nop 0
	v_mfma_f32_32x32x16_bf16 v[64:79], v[144:147], v[182:185], v[64:79]
	v_mfma_f32_32x32x16_bf16 v[32:47], v[144:147], v[186:189], v[32:47]
	v_mfma_f32_32x32x16_bf16 v[0:15], v[144:147], v[190:193], v[0:15]
	v_mfma_f32_32x32x16_bf16 v[80:95], v[148:151], v[182:185], v[80:95]
	v_mfma_f32_32x32x16_bf16 v[48:63], v[148:151], v[186:189], v[48:63]
	v_mfma_f32_32x32x16_bf16 v[16:31], v[148:151], v[190:193], v[16:31]
	v_add_u32_e32 v115, v115, v107
	ds_read_b128 v[144:147], v115 offset:0
	ds_read_b128 v[148:151], v115 offset:0x1000
	v_add_u32_e32 v115, v128, v107
	ds_read_b128 v[182:185], v115 offset:0
	ds_read_b128 v[186:189], v115 offset:0x1000
	ds_read_b128 v[190:193], v115 offset:0x2000
	s_waitcnt lgkmcnt(5)
	s_nop 0
	v_mfma_f32_32x32x16_bf16 v[64:79], v[116:119], v[124:127], v[64:79]
	v_mfma_f32_32x32x16_bf16 v[32:47], v[116:119], v[130:133], v[32:47]
	v_mfma_f32_32x32x16_bf16 v[0:15], v[116:119], v[134:137], v[0:15]
	v_mfma_f32_32x32x16_bf16 v[80:95], v[120:123], v[124:127], v[80:95]
	v_mfma_f32_32x32x16_bf16 v[48:63], v[120:123], v[130:133], v[48:63]
	v_mfma_f32_32x32x16_bf16 v[16:31], v[120:123], v[134:137], v[16:31]
	s_waitcnt lgkmcnt(0)
	s_nop 0
	v_mfma_f32_32x32x16_bf16 v[64:79], v[144:147], v[182:185], v[64:79]
	v_mfma_f32_32x32x16_bf16 v[32:47], v[144:147], v[186:189], v[32:47]
	v_mfma_f32_32x32x16_bf16 v[0:15], v[144:147], v[190:193], v[0:15]
	v_mfma_f32_32x32x16_bf16 v[80:95], v[148:151], v[182:185], v[80:95]
	v_mfma_f32_32x32x16_bf16 v[48:63], v[148:151], v[186:189], v[48:63]
	v_mfma_f32_32x32x16_bf16 v[16:31], v[148:151], v[190:193], v[16:31]
	s_add_u32 s2, s2, 0x80
	s_addc_u32 s3, s3, 0
	s_cmpk_eq_i32 s2, 0x1f80
	s_mov_b32 s7, s9
	s_cbranch_scc0 .LBB0_1434
	s_waitcnt vmcnt(0)
	s_waitcnt vmcnt(0) lgkmcnt(0)
	s_barrier
	v_add_u32_e32 v109, 0x14000, v112
	v_add_u32_e32 v112, v109, v111
	ds_read_b128 v[96:99], v112 offset:0
	v_add_u32_e32 v128, 0xe000, v113
	ds_read_b128 v[112:115], v112 offset:0x1000
	v_add_u32_e32 v111, v128, v111
	ds_read_b128 v[116:119], v111 offset:0
	ds_read_b128 v[120:123], v111 offset:0x1000
	ds_read_b128 v[124:127], v111 offset:0x2000
	v_add_u32_e32 v111, v109, v110
	ds_read_b128 v[130:133], v111 offset:0
	ds_read_b128 v[134:137], v111 offset:0x1000
	v_add_u32_e32 v110, v128, v110
	ds_read_b128 v[144:147], v110 offset:0
	ds_read_b128 v[148:151], v110 offset:0x1000
	ds_read_b128 v[182:185], v110 offset:0x2000
	s_waitcnt lgkmcnt(5)
	s_nop 0
	v_mfma_f32_32x32x16_bf16 v[64:79], v[96:99], v[116:119], v[64:79]
	v_mfma_f32_32x32x16_bf16 v[32:47], v[96:99], v[120:123], v[32:47]
	v_mfma_f32_32x32x16_bf16 v[0:15], v[96:99], v[124:127], v[0:15]
	v_mfma_f32_32x32x16_bf16 v[48:63], v[112:115], v[120:123], v[48:63]
	v_mfma_f32_32x32x16_bf16 v[16:31], v[112:115], v[124:127], v[16:31]
	v_mfma_f32_32x32x16_bf16 v[80:95], v[112:115], v[116:119], v[80:95]
	v_add_u32_e32 v110, v109, v108
	ds_read_b128 v[96:99], v110 offset:0
	ds_read_b128 v[110:113], v110 offset:0x1000
	v_add_u32_e32 v108, v128, v108
	ds_read_b128 v[114:117], v108 offset:0
	ds_read_b128 v[118:121], v108 offset:0x1000
	ds_read_b128 v[122:125], v108 offset:0x2000
	s_waitcnt lgkmcnt(5)
	s_nop 0
	v_mfma_f32_32x32x16_bf16 v[64:79], v[130:133], v[144:147], v[64:79]
	v_mfma_f32_32x32x16_bf16 v[32:47], v[130:133], v[148:151], v[32:47]
	v_mfma_f32_32x32x16_bf16 v[0:15], v[130:133], v[182:185], v[0:15]
	v_mfma_f32_32x32x16_bf16 v[48:63], v[134:137], v[148:151], v[48:63]
	v_mfma_f32_32x32x16_bf16 v[16:31], v[134:137], v[182:185], v[16:31]
	v_mfma_f32_32x32x16_bf16 v[80:95], v[134:137], v[144:147], v[80:95]
	v_add_u32_e32 v108, v109, v107
	ds_read_b128 v[130:133], v108 offset:0
	ds_read_b128 v[134:137], v108 offset:0x1000
	v_add_u32_e32 v107, v128, v107
	ds_read_b128 v[144:147], v107 offset:0
	ds_read_b128 v[148:151], v107 offset:0x1000
	ds_read_b128 v[182:185], v107 offset:0x2000
	s_waitcnt lgkmcnt(5)
	s_nop 0
	v_mfma_f32_32x32x16_bf16 v[64:79], v[96:99], v[114:117], v[64:79]
	v_mfma_f32_32x32x16_bf16 v[32:47], v[96:99], v[118:121], v[32:47]
	v_mfma_f32_32x32x16_bf16 v[0:15], v[96:99], v[122:125], v[0:15]
	v_mfma_f32_32x32x16_bf16 v[48:63], v[110:113], v[118:121], v[48:63]
	v_mfma_f32_32x32x16_bf16 v[16:31], v[110:113], v[122:125], v[16:31]
	v_mfma_f32_32x32x16_bf16 v[80:95], v[110:113], v[114:117], v[80:95]
	s_waitcnt lgkmcnt(0)
	s_nop 0
	v_mfma_f32_32x32x16_bf16 v[64:79], v[130:133], v[144:147], v[64:79]
	v_mfma_f32_32x32x16_bf16 v[32:47], v[130:133], v[148:151], v[32:47]
	v_mfma_f32_32x32x16_bf16 v[0:15], v[130:133], v[182:185], v[0:15]
	v_mfma_f32_32x32x16_bf16 v[48:63], v[134:137], v[148:151], v[48:63]
	v_mfma_f32_32x32x16_bf16 v[16:31], v[134:137], v[182:185], v[16:31]
	v_mfma_f32_32x32x16_bf16 v[80:95], v[134:137], v[144:147], v[80:95]
	v_add_u32_e32 v96, s4, v106
	v_lshrrev_b32_e32 v128, 4, v101
	v_and_b32_e32 v112, 15, v100
	v_or_b32_e32 v100, v96, v128
	v_add_u32_e32 v105, s8, v105
	v_ashrrev_i32_e32 v101, 31, v100
	v_lshl_or_b32 v98, v112, 2, v105
	v_lshlrev_b64 v[106:107], 12, v[100:101]
	v_ashrrev_i32_e32 v99, 31, v98
	v_lshl_add_u64 v[106:107], s[40:41], 0, v[106:107]
	v_lshl_add_u64 v[110:111], v[98:99], 2, v[106:107]
	s_barrier
	global_load_dwordx4 v[198:201], v[110:111], off
	v_add_co_u32_e32 v182, vcc, 0x4000, v110
	s_nop 1
	v_addc_co_u32_e32 v183, vcc, 0, v111, vcc
	global_load_dwordx4 v[202:205], v[182:183], off
	v_add_co_u32_e32 v182, vcc, 0x4000, v182
	s_nop 1
	v_addc_co_u32_e32 v183, vcc, 0, v183, vcc
	global_load_dwordx4 v[206:209], v[182:183], off
	v_add_co_u32_e32 v182, vcc, 0x4000, v182
	s_nop 1
	v_addc_co_u32_e32 v183, vcc, 0, v183, vcc
	global_load_dwordx4 v[210:213], v[182:183], off
	v_add_co_u32_e32 v182, vcc, 0x4000, v182
	s_nop 1
	v_addc_co_u32_e32 v183, vcc, 0, v183, vcc
	global_load_dwordx4 v[214:217], v[182:183], off
	v_add_co_u32_e32 v182, vcc, 0x4000, v182
	s_nop 1
	v_addc_co_u32_e32 v183, vcc, 0, v183, vcc
	global_load_dwordx4 v[218:221], v[182:183], off
	v_add_co_u32_e32 v182, vcc, 0x4000, v182
	s_nop 1
	v_addc_co_u32_e32 v183, vcc, 0, v183, vcc
	global_load_dwordx4 v[222:225], v[182:183], off
	v_add_co_u32_e32 v182, vcc, 0x4000, v182
	s_nop 1
	v_addc_co_u32_e32 v183, vcc, 0, v183, vcc
	global_load_dwordx4 v[226:229], v[182:183], off
	s_movk_i32 s2, 0x2400
	s_cmp_lt_i32 s5, 22
	v_mul_lo_u32 v97, v103, s2
	s_cselect_b64 s[2:3], -1, 0
	s_cmp_gt_i32 s5, 21
	s_movk_i32 s5, 0x110
	v_and_b32_e32 v103, 16, v104
	v_mad_u32_u24 v104, v102, s5, v97
	v_add_u32_e32 v113, 0xfffff000, v96
	v_cndmask_b32_e64 v102, 0, 1, s[2:3]
	s_cselect_b64 s[2:3], -1, 0
	s_add_i32 s7, s4, 0xfffff000
	v_add_u32_e32 v104, v104, v103
	ds_write_b128 v104, v[64:67]
	ds_write_b128 v104, v[68:71] offset:32
	ds_write_b128 v104, v[72:75] offset:64
	ds_write_b128 v104, v[76:79] offset:96
	ds_write_b128 v104, v[80:83] offset:128
	ds_write_b128 v104, v[84:87] offset:160
	ds_write_b128 v104, v[88:91] offset:192
	ds_write_b128 v104, v[92:95] offset:224
	v_xor_b32_e32 v64, s7, v113
	s_movk_i32 s4, 0x400
	v_lshl_or_b32 v97, v112, 4, v97
	v_cmp_gt_u32_e32 vcc, s4, v64
	v_mad_u32_u24 v115, v128, s5, v97
	s_and_b64 s[4:5], s[2:3], vcc
	v_cndmask_b32_e64 v71, 0, 1, s[4:5]
	s_movk_i32 s4, 0x1000
	v_cmp_gt_i32_e32 vcc, s4, v100
	v_subrev_u32_e32 v114, s8, v98
	v_lshl_add_u32 v103, v114, 2, v167
	v_cndmask_b32_e32 v64, v71, v102, vcc
	v_and_b32_e32 v64, 1, v64
	v_cmp_eq_u32_e32 vcc, 1, v64
	v_ashrrev_i32_e32 v68, 6, v105
	s_mov_b32 s4, 0xc000
	v_cndmask_b32_e64 v64, v171, 0, vcc
	v_add_u32_e32 v70, v103, v64
	ds_read_b128 v[64:67], v115
	ds_read_b128 v[72:75], v70
	v_cmp_eq_u32_e64 s[36:37], 0, v112
	v_mad_i64_i32 v[68:69], s[4:5], v68, s4, 0
	s_and_b64 vcc, exec, s[0:1]
	s_waitcnt vmcnt(7) lgkmcnt(0)
	v_pk_fma_f32 v[66:67], v[66:67], v[74:75], v[200:201]
	v_pk_fma_f32 v[64:65], v[64:65], v[72:73], v[198:199]
	global_store_dwordx4 v[110:111], v[64:67], off
	s_cbranch_vccnz .LBB0_1439
	ds_read_b128 v[72:75], v70 offset:2048
	v_lshlrev_b64 v[76:77], 10, v[100:101]
	v_lshl_add_u64 v[76:77], v[76:77], 1, s[50:51]
	v_lshl_add_u64 v[76:77], v[98:99], 1, v[76:77]
	s_waitcnt lgkmcnt(0)
	v_pk_mul_f32 v[72:73], v[64:65], v[72:73]
	v_pk_mul_f32 v[64:65], v[64:65], v[64:65]
	v_pk_mul_f32 v[74:75], v[66:67], v[74:75]
	v_pk_mul_f32 v[66:67], v[66:67], v[66:67]
	v_add_f32_e32 v64, v64, v65
	v_add_f32_e32 v64, v66, v64
	v_add_f32_e32 v64, v67, v64
	v_cvt_pk_bf16_f32 v72, v72, v73
	v_cvt_pk_bf16_f32 v73, v74, v75
	v_add_f32_dpp v64, v64, v64 quad_perm:[1,0,3,2] row_mask:0xf bank_mask:0xf bound_ctrl:1
	global_store_dwordx2 v[76:77], v[72:73], off
	s_nop 0
	v_add_f32_dpp v64, v64, v64 quad_perm:[2,3,0,1] row_mask:0xf bank_mask:0xf bound_ctrl:1
	s_nop 1
	v_add_f32_dpp v64, v64, v64 row_half_mirror row_mask:0xf bank_mask:0xf bound_ctrl:1
	s_nop 1
	v_mov_b32_dpp v65, v64 row_mirror row_mask:0xf bank_mask:0xf bound_ctrl:1
	s_and_saveexec_b64 s[4:5], s[36:37]
	s_cbranch_execz .LBB0_1438
	v_lshl_add_u64 v[66:67], s[54:55], 0, v[68:69]
	v_lshl_add_u64 v[66:67], v[100:101], 2, v[66:67]
	v_add_f32_e32 v64, v64, v65
	global_store_dword v[66:67], v64, off

.LBB0_1439:
	v_or_b32_e32 v70, 4, v128
	v_or_b32_e32 v72, v96, v70
	v_ashrrev_i32_e32 v73, 31, v72
	v_lshlrev_b64 v[64:65], 12, v[72:73]
	v_lshl_add_u64 v[64:65], s[40:41], 0, v[64:65]
	v_lshl_add_u64 v[84:85], v[98:99], 2, v[64:65]
	s_movk_i32 s4, 0x1000
	v_mul_u32_u24_e32 v74, 0x110, v128
	v_cmp_gt_i32_e32 vcc, s4, v72
	v_add_u32_e32 v86, v74, v97
	s_nop 0
	v_cndmask_b32_e32 v74, v71, v102, vcc
	v_and_b32_e32 v74, 1, v74
	v_cmp_eq_u32_e32 vcc, 1, v74
	s_nop 1
	v_cndmask_b32_e64 v74, v171, 0, vcc
	v_add_u32_e32 v74, v103, v74
	ds_read_b128 v[76:79], v86 offset:1088
	ds_read_b128 v[80:83], v74
	s_and_b64 vcc, exec, s[0:1]
	s_waitcnt vmcnt(7) lgkmcnt(0)
	v_pk_fma_f32 v[66:67], v[78:79], v[82:83], v[204:205]
	v_pk_fma_f32 v[64:65], v[76:77], v[80:81], v[202:203]
	global_store_dwordx4 v[84:85], v[64:67], off
	s_cbranch_vccnz .LBB0_1443
	ds_read_b128 v[74:77], v74 offset:2048
	v_lshlrev_b64 v[72:73], 10, v[72:73]
	v_lshl_add_u64 v[72:73], v[72:73], 1, s[50:51]
	v_lshl_add_u64 v[72:73], v[98:99], 1, v[72:73]
	s_waitcnt lgkmcnt(0)
	v_pk_mul_f32 v[74:75], v[64:65], v[74:75]
	v_pk_mul_f32 v[64:65], v[64:65], v[64:65]
	v_pk_mul_f32 v[76:77], v[66:67], v[76:77]
	v_pk_mul_f32 v[66:67], v[66:67], v[66:67]
	v_add_f32_e32 v64, v64, v65
	v_add_f32_e32 v64, v66, v64
	v_add_f32_e32 v64, v67, v64
	v_cvt_pk_bf16_f32 v74, v74, v75
	v_cvt_pk_bf16_f32 v75, v76, v77
	v_add_f32_dpp v64, v64, v64 quad_perm:[1,0,3,2] row_mask:0xf bank_mask:0xf bound_ctrl:1
	global_store_dwordx2 v[72:73], v[74:75], off
	s_nop 0
	v_add_f32_dpp v64, v64, v64 quad_perm:[2,3,0,1] row_mask:0xf bank_mask:0xf bound_ctrl:1
	s_nop 1
	v_add_f32_dpp v64, v64, v64 row_half_mirror row_mask:0xf bank_mask:0xf bound_ctrl:1
	s_nop 1
	v_mov_b32_dpp v65, v64 row_mirror row_mask:0xf bank_mask:0xf bound_ctrl:1
	s_and_saveexec_b64 s[4:5], s[36:37]
	s_cbranch_execz .LBB0_1442
	v_ashrrev_i32_e32 v97, 31, v96
	v_lshl_add_u64 v[66:67], s[54:55], 0, v[68:69]
	v_lshl_add_u64 v[72:73], v[96:97], 0, v[128:129]
	v_lshl_add_u64 v[66:67], v[72:73], 2, v[66:67]
	v_add_f32_e32 v64, v64, v65
	global_store_dword v[66:67], v64, off offset:16

.LBB0_1443:
	v_or_b32_e32 v72, 8, v128
	v_or_b32_e32 v74, v96, v72
	v_ashrrev_i32_e32 v75, 31, v74
	v_lshlrev_b64 v[64:65], 12, v[74:75]
	v_lshl_add_u64 v[64:65], s[40:41], 0, v[64:65]
	v_lshl_add_u64 v[84:85], v[98:99], 2, v[64:65]
	s_movk_i32 s4, 0x1000
	v_cmp_gt_i32_e32 vcc, s4, v74
	s_nop 1
	v_cndmask_b32_e32 v73, v71, v102, vcc
	v_and_b32_e32 v73, 1, v73
	v_cmp_eq_u32_e32 vcc, 1, v73
	s_nop 1
	v_cndmask_b32_e64 v73, v171, 0, vcc
	v_add_u32_e32 v73, v103, v73
	ds_read_b128 v[76:79], v86 offset:2176
	ds_read_b128 v[80:83], v73
	s_and_b64 vcc, exec, s[0:1]
	s_waitcnt vmcnt(7) lgkmcnt(0)
	v_pk_fma_f32 v[66:67], v[78:79], v[82:83], v[208:209]
	v_pk_fma_f32 v[64:65], v[76:77], v[80:81], v[206:207]
	global_store_dwordx4 v[84:85], v[64:67], off
	s_cbranch_vccnz .LBB0_1447
	ds_read_b128 v[76:79], v73 offset:2048
	v_lshlrev_b64 v[74:75], 10, v[74:75]
	v_lshl_add_u64 v[74:75], v[74:75], 1, s[50:51]
	v_lshl_add_u64 v[74:75], v[98:99], 1, v[74:75]
	s_waitcnt lgkmcnt(0)
	v_pk_mul_f32 v[76:77], v[64:65], v[76:77]
	v_pk_mul_f32 v[64:65], v[64:65], v[64:65]
	v_pk_mul_f32 v[78:79], v[66:67], v[78:79]
	v_pk_mul_f32 v[66:67], v[66:67], v[66:67]
	v_add_f32_e32 v64, v64, v65
	v_add_f32_e32 v64, v66, v64
	v_add_f32_e32 v64, v67, v64
	v_cvt_pk_bf16_f32 v76, v76, v77
	v_cvt_pk_bf16_f32 v77, v78, v79
	v_add_f32_dpp v64, v64, v64 quad_perm:[1,0,3,2] row_mask:0xf bank_mask:0xf bound_ctrl:1
	global_store_dwordx2 v[74:75], v[76:77], off
	s_nop 0
	v_add_f32_dpp v64, v64, v64 quad_perm:[2,3,0,1] row_mask:0xf bank_mask:0xf bound_ctrl:1
	s_nop 1
	v_add_f32_dpp v64, v64, v64 row_half_mirror row_mask:0xf bank_mask:0xf bound_ctrl:1
	s_nop 1
	v_mov_b32_dpp v65, v64 row_mirror row_mask:0xf bank_mask:0xf bound_ctrl:1
	s_and_saveexec_b64 s[4:5], s[36:37]
	s_cbranch_execz .LBB0_1446
	v_ashrrev_i32_e32 v97, 31, v96
	v_lshl_add_u64 v[66:67], s[54:55], 0, v[68:69]
	v_lshl_add_u64 v[74:75], v[96:97], 0, v[128:129]
	v_lshl_add_u64 v[66:67], v[74:75], 2, v[66:67]
	v_add_f32_e32 v64, v64, v65
	global_store_dword v[66:67], v64, off offset:32

.LBB0_1447:
	v_or_b32_e32 v74, 12, v128
	v_or_b32_e32 v76, v96, v74
	v_ashrrev_i32_e32 v77, 31, v76
	v_lshlrev_b64 v[64:65], 12, v[76:77]
	v_lshl_add_u64 v[64:65], s[40:41], 0, v[64:65]
	v_lshl_add_u64 v[88:89], v[98:99], 2, v[64:65]
	s_movk_i32 s4, 0x1000
	v_cmp_gt_i32_e32 vcc, s4, v76
	s_nop 1
	v_cndmask_b32_e32 v73, v71, v102, vcc
	v_and_b32_e32 v73, 1, v73
	v_cmp_eq_u32_e32 vcc, 1, v73
	s_nop 1
	v_cndmask_b32_e64 v73, v171, 0, vcc
	v_add_u32_e32 v73, v103, v73
	ds_read_b128 v[78:81], v86 offset:3264
	ds_read_b128 v[82:85], v73
	s_and_b64 vcc, exec, s[0:1]
	s_waitcnt vmcnt(7) lgkmcnt(0)
	v_pk_fma_f32 v[66:67], v[80:81], v[84:85], v[212:213]
	v_pk_fma_f32 v[64:65], v[78:79], v[82:83], v[210:211]
	global_store_dwordx4 v[88:89], v[64:67], off
	s_cbranch_vccnz .LBB0_1451
	ds_read_b128 v[78:81], v73 offset:2048
	v_lshlrev_b64 v[76:77], 10, v[76:77]
	v_lshl_add_u64 v[76:77], v[76:77], 1, s[50:51]
	v_lshl_add_u64 v[76:77], v[98:99], 1, v[76:77]
	s_waitcnt lgkmcnt(0)
	v_pk_mul_f32 v[78:79], v[64:65], v[78:79]
	v_pk_mul_f32 v[64:65], v[64:65], v[64:65]
	v_pk_mul_f32 v[80:81], v[66:67], v[80:81]
	v_pk_mul_f32 v[66:67], v[66:67], v[66:67]
	v_add_f32_e32 v64, v64, v65
	v_add_f32_e32 v64, v66, v64
	v_add_f32_e32 v64, v67, v64
	v_cvt_pk_bf16_f32 v78, v78, v79
	v_cvt_pk_bf16_f32 v79, v80, v81
	v_add_f32_dpp v64, v64, v64 quad_perm:[1,0,3,2] row_mask:0xf bank_mask:0xf bound_ctrl:1
	global_store_dwordx2 v[76:77], v[78:79], off
	s_nop 0
	v_add_f32_dpp v64, v64, v64 quad_perm:[2,3,0,1] row_mask:0xf bank_mask:0xf bound_ctrl:1
	s_nop 1
	v_add_f32_dpp v64, v64, v64 row_half_mirror row_mask:0xf bank_mask:0xf bound_ctrl:1
	s_nop 1
	v_mov_b32_dpp v65, v64 row_mirror row_mask:0xf bank_mask:0xf bound_ctrl:1
	s_and_saveexec_b64 s[4:5], s[36:37]
	s_cbranch_execz .LBB0_1450
	v_ashrrev_i32_e32 v97, 31, v96
	v_lshl_add_u64 v[66:67], s[54:55], 0, v[68:69]
	v_lshl_add_u64 v[76:77], v[96:97], 0, v[128:129]
	v_lshl_add_u64 v[66:67], v[76:77], 2, v[66:67]
	v_add_f32_e32 v64, v64, v65
	global_store_dword v[66:67], v64, off offset:48

.LBB0_1451:
	v_or_b32_e32 v76, 16, v128
	v_or_b32_e32 v78, v96, v76
	v_ashrrev_i32_e32 v79, 31, v78
	v_lshlrev_b64 v[64:65], 12, v[78:79]
	v_lshl_add_u64 v[64:65], s[40:41], 0, v[64:65]
	v_lshl_add_u64 v[84:85], v[98:99], 2, v[64:65]
	s_movk_i32 s4, 0x1000
	v_cmp_gt_i32_e32 vcc, s4, v78
	s_nop 1
	v_cndmask_b32_e32 v73, v71, v102, vcc
	v_and_b32_e32 v73, 1, v73
	v_cmp_eq_u32_e32 vcc, 1, v73
	s_nop 1
	v_cndmask_b32_e64 v73, v171, 0, vcc
	v_add_u32_e32 v73, v103, v73
	ds_read_b128 v[80:83], v86 offset:4352
	ds_read_b128 v[88:91], v73
	s_and_b64 vcc, exec, s[0:1]
	s_waitcnt vmcnt(7) lgkmcnt(0)
	v_pk_fma_f32 v[66:67], v[82:83], v[90:91], v[216:217]
	v_pk_fma_f32 v[64:65], v[80:81], v[88:89], v[214:215]
	global_store_dwordx4 v[84:85], v[64:67], off
	s_cbranch_vccnz .LBB0_1455
	ds_read_b128 v[80:83], v73 offset:2048
	v_lshlrev_b64 v[78:79], 10, v[78:79]
	v_lshl_add_u64 v[78:79], v[78:79], 1, s[50:51]
	v_lshl_add_u64 v[78:79], v[98:99], 1, v[78:79]
	s_waitcnt lgkmcnt(0)
	v_pk_mul_f32 v[80:81], v[64:65], v[80:81]
	v_pk_mul_f32 v[64:65], v[64:65], v[64:65]
	v_pk_mul_f32 v[82:83], v[66:67], v[82:83]
	v_pk_mul_f32 v[66:67], v[66:67], v[66:67]
	v_add_f32_e32 v64, v64, v65
	v_add_f32_e32 v64, v66, v64
	v_add_f32_e32 v64, v67, v64
	v_cvt_pk_bf16_f32 v80, v80, v81
	v_cvt_pk_bf16_f32 v81, v82, v83
	v_add_f32_dpp v64, v64, v64 quad_perm:[1,0,3,2] row_mask:0xf bank_mask:0xf bound_ctrl:1
	global_store_dwordx2 v[78:79], v[80:81], off
	s_nop 0
	v_add_f32_dpp v64, v64, v64 quad_perm:[2,3,0,1] row_mask:0xf bank_mask:0xf bound_ctrl:1
	s_nop 1
	v_add_f32_dpp v64, v64, v64 row_half_mirror row_mask:0xf bank_mask:0xf bound_ctrl:1
	s_nop 1
	v_mov_b32_dpp v65, v64 row_mirror row_mask:0xf bank_mask:0xf bound_ctrl:1
	s_and_saveexec_b64 s[4:5], s[36:37]
	s_cbranch_execz .LBB0_1454
	v_ashrrev_i32_e32 v97, 31, v96
	v_lshl_add_u64 v[66:67], s[54:55], 0, v[68:69]
	v_lshl_add_u64 v[78:79], v[96:97], 0, v[128:129]
	v_lshl_add_u64 v[66:67], v[78:79], 2, v[66:67]
	v_add_f32_e32 v64, v64, v65
	global_store_dword v[66:67], v64, off offset:64

.LBB0_1455:
	v_or_b32_e32 v78, 20, v128
	v_or_b32_e32 v80, v96, v78
	v_ashrrev_i32_e32 v81, 31, v80
	v_lshlrev_b64 v[64:65], 12, v[80:81]
	v_lshl_add_u64 v[64:65], s[40:41], 0, v[64:65]
	v_lshl_add_u64 v[92:93], v[98:99], 2, v[64:65]
	s_movk_i32 s4, 0x1000
	v_cmp_gt_i32_e32 vcc, s4, v80
	s_nop 1
	v_cndmask_b32_e32 v73, v71, v102, vcc
	v_and_b32_e32 v73, 1, v73
	v_cmp_eq_u32_e32 vcc, 1, v73
	s_nop 1
	v_cndmask_b32_e64 v73, v171, 0, vcc
	v_add_u32_e32 v73, v103, v73
	ds_read_b128 v[82:85], v86 offset:5440
	ds_read_b128 v[88:91], v73
	s_and_b64 vcc, exec, s[0:1]
	s_waitcnt vmcnt(7) lgkmcnt(0)
	v_pk_fma_f32 v[66:67], v[84:85], v[90:91], v[220:221]
	v_pk_fma_f32 v[64:65], v[82:83], v[88:89], v[218:219]
	global_store_dwordx4 v[92:93], v[64:67], off
	s_cbranch_vccnz .LBB0_1459
	ds_read_b128 v[82:85], v73 offset:2048
	v_lshlrev_b64 v[80:81], 10, v[80:81]
	v_lshl_add_u64 v[80:81], v[80:81], 1, s[50:51]
	v_lshl_add_u64 v[80:81], v[98:99], 1, v[80:81]
	s_waitcnt lgkmcnt(0)
	v_pk_mul_f32 v[82:83], v[64:65], v[82:83]
	v_pk_mul_f32 v[64:65], v[64:65], v[64:65]
	v_pk_mul_f32 v[84:85], v[66:67], v[84:85]
	v_pk_mul_f32 v[66:67], v[66:67], v[66:67]
	v_add_f32_e32 v64, v64, v65
	v_add_f32_e32 v64, v66, v64
	v_add_f32_e32 v64, v67, v64
	v_cvt_pk_bf16_f32 v82, v82, v83
	v_cvt_pk_bf16_f32 v83, v84, v85
	v_add_f32_dpp v64, v64, v64 quad_perm:[1,0,3,2] row_mask:0xf bank_mask:0xf bound_ctrl:1
	global_store_dwordx2 v[80:81], v[82:83], off
	s_nop 0
	v_add_f32_dpp v64, v64, v64 quad_perm:[2,3,0,1] row_mask:0xf bank_mask:0xf bound_ctrl:1
	s_nop 1
	v_add_f32_dpp v64, v64, v64 row_half_mirror row_mask:0xf bank_mask:0xf bound_ctrl:1
	s_nop 1
	v_mov_b32_dpp v65, v64 row_mirror row_mask:0xf bank_mask:0xf bound_ctrl:1
	s_and_saveexec_b64 s[4:5], s[36:37]
	s_cbranch_execz .LBB0_1458
	v_ashrrev_i32_e32 v97, 31, v96
	v_lshl_add_u64 v[66:67], s[54:55], 0, v[68:69]
	v_lshl_add_u64 v[80:81], v[96:97], 0, v[128:129]
	v_lshl_add_u64 v[66:67], v[80:81], 2, v[66:67]
	v_add_f32_e32 v64, v64, v65
	global_store_dword v[66:67], v64, off offset:80

.LBB0_1459:
	v_or_b32_e32 v80, 24, v128
	v_or_b32_e32 v82, v96, v80
	v_ashrrev_i32_e32 v83, 31, v82
	v_lshlrev_b64 v[64:65], 12, v[82:83]
	v_lshl_add_u64 v[64:65], s[40:41], 0, v[64:65]
	v_lshl_add_u64 v[84:85], v[98:99], 2, v[64:65]
	s_movk_i32 s4, 0x1000
	v_cmp_gt_i32_e32 vcc, s4, v82
	s_nop 1
	v_cndmask_b32_e32 v73, v71, v102, vcc
	v_and_b32_e32 v73, 1, v73
	v_cmp_eq_u32_e32 vcc, 1, v73
	s_nop 1
	v_cndmask_b32_e64 v73, v171, 0, vcc
	v_add_u32_e32 v73, v103, v73
	ds_read_b128 v[88:91], v86 offset:6528
	ds_read_b128 v[92:95], v73
	s_and_b64 vcc, exec, s[0:1]
	s_waitcnt vmcnt(7) lgkmcnt(0)
	v_pk_fma_f32 v[66:67], v[90:91], v[94:95], v[224:225]
	v_pk_fma_f32 v[64:65], v[88:89], v[92:93], v[222:223]
	global_store_dwordx4 v[84:85], v[64:67], off
	s_cbranch_vccnz .LBB0_1463
	ds_read_b128 v[88:91], v73 offset:2048
	v_lshlrev_b64 v[82:83], 10, v[82:83]
	v_lshl_add_u64 v[82:83], v[82:83], 1, s[50:51]
	v_lshl_add_u64 v[82:83], v[98:99], 1, v[82:83]
	s_waitcnt lgkmcnt(0)
	v_pk_mul_f32 v[88:89], v[64:65], v[88:89]
	v_pk_mul_f32 v[64:65], v[64:65], v[64:65]
	v_pk_mul_f32 v[84:85], v[66:67], v[90:91]
	v_pk_mul_f32 v[66:67], v[66:67], v[66:67]
	v_add_f32_e32 v64, v64, v65
	v_add_f32_e32 v64, v66, v64
	v_add_f32_e32 v64, v67, v64
	v_cvt_pk_bf16_f32 v88, v88, v89
	v_cvt_pk_bf16_f32 v89, v84, v85
	v_add_f32_dpp v64, v64, v64 quad_perm:[1,0,3,2] row_mask:0xf bank_mask:0xf bound_ctrl:1
	global_store_dwordx2 v[82:83], v[88:89], off
	s_nop 0
	v_add_f32_dpp v64, v64, v64 quad_perm:[2,3,0,1] row_mask:0xf bank_mask:0xf bound_ctrl:1
	s_nop 1
	v_add_f32_dpp v64, v64, v64 row_half_mirror row_mask:0xf bank_mask:0xf bound_ctrl:1
	s_nop 1
	v_mov_b32_dpp v65, v64 row_mirror row_mask:0xf bank_mask:0xf bound_ctrl:1
	s_and_saveexec_b64 s[4:5], s[36:37]
	s_cbranch_execz .LBB0_1462
	v_ashrrev_i32_e32 v97, 31, v96
	v_lshl_add_u64 v[66:67], s[54:55], 0, v[68:69]
	v_lshl_add_u64 v[82:83], v[96:97], 0, v[128:129]
	v_lshl_add_u64 v[66:67], v[82:83], 2, v[66:67]
	v_add_f32_e32 v64, v64, v65
	global_store_dword v[66:67], v64, off offset:96

.LBB0_1463:
	v_or_b32_e32 v82, 28, v128
	v_or_b32_e32 v84, v96, v82
	v_ashrrev_i32_e32 v85, 31, v84
	v_lshlrev_b64 v[64:65], 12, v[84:85]
	v_lshl_add_u64 v[64:65], s[40:41], 0, v[64:65]
	v_lshl_add_u64 v[100:101], v[98:99], 2, v[64:65]
	s_movk_i32 s4, 0x1000
	v_cmp_gt_i32_e32 vcc, s4, v84
	s_nop 1
	v_cndmask_b32_e32 v71, v71, v102, vcc
	v_and_b32_e32 v71, 1, v71
	v_cmp_eq_u32_e32 vcc, 1, v71
	s_nop 1
	v_cndmask_b32_e64 v71, v171, 0, vcc
	v_add_u32_e32 v71, v103, v71
	ds_read_b128 v[88:91], v86 offset:7616
	ds_read_b128 v[92:95], v71
	s_and_b64 vcc, exec, s[0:1]
	s_waitcnt vmcnt(7) lgkmcnt(0)
	v_pk_fma_f32 v[66:67], v[90:91], v[94:95], v[228:229]
	v_pk_fma_f32 v[64:65], v[88:89], v[92:93], v[226:227]
	global_store_dwordx4 v[100:101], v[64:67], off
	s_cbranch_vccnz .LBB0_1467
	ds_read_b128 v[88:91], v71 offset:2048
	v_lshlrev_b64 v[84:85], 10, v[84:85]
	v_lshl_add_u64 v[84:85], v[84:85], 1, s[50:51]
	v_lshl_add_u64 v[84:85], v[98:99], 1, v[84:85]
	s_waitcnt lgkmcnt(0)
	v_pk_mul_f32 v[88:89], v[64:65], v[88:89]
	v_pk_mul_f32 v[64:65], v[64:65], v[64:65]
	v_pk_mul_f32 v[90:91], v[66:67], v[90:91]
	v_pk_mul_f32 v[66:67], v[66:67], v[66:67]
	v_add_f32_e32 v64, v64, v65
	v_add_f32_e32 v64, v66, v64
	v_add_f32_e32 v64, v67, v64
	v_cvt_pk_bf16_f32 v88, v88, v89
	v_cvt_pk_bf16_f32 v89, v90, v91
	v_add_f32_dpp v64, v64, v64 quad_perm:[1,0,3,2] row_mask:0xf bank_mask:0xf bound_ctrl:1
	global_store_dwordx2 v[84:85], v[88:89], off
	s_nop 0
	v_add_f32_dpp v64, v64, v64 quad_perm:[2,3,0,1] row_mask:0xf bank_mask:0xf bound_ctrl:1
	s_nop 1
	v_add_f32_dpp v64, v64, v64 row_half_mirror row_mask:0xf bank_mask:0xf bound_ctrl:1
	s_nop 1
	v_mov_b32_dpp v65, v64 row_mirror row_mask:0xf bank_mask:0xf bound_ctrl:1
	s_and_saveexec_b64 s[4:5], s[36:37]
	s_cbranch_execz .LBB0_1466
	v_ashrrev_i32_e32 v97, 31, v96
	v_lshl_add_u64 v[66:67], s[54:55], 0, v[68:69]
	v_lshl_add_u64 v[84:85], v[96:97], 0, v[128:129]
	v_lshl_add_u64 v[66:67], v[84:85], 2, v[66:67]
	v_add_f32_e32 v64, v64, v65
	global_store_dword v[66:67], v64, off offset:112

.LBB0_1467:
	s_nop 0
	v_add_u32_e32 v66, 32, v96
	v_or_b32_e32 v64, v66, v128
	v_ashrrev_i32_e32 v65, 31, v64
	v_lshlrev_b64 v[84:85], 12, v[64:65]
	v_lshl_add_u64 v[84:85], s[40:41], 0, v[84:85]
	v_lshl_add_u64 v[84:85], v[98:99], 2, v[84:85]
	global_load_dwordx4 v[198:201], v[84:85], off
	v_add_co_u32_e32 v182, vcc, 0x4000, v84
	s_nop 1
	v_addc_co_u32_e32 v183, vcc, 0, v85, vcc
	global_load_dwordx4 v[202:205], v[182:183], off
	v_add_co_u32_e32 v182, vcc, 0x4000, v182
	s_nop 1
	v_addc_co_u32_e32 v183, vcc, 0, v183, vcc
	global_load_dwordx4 v[206:209], v[182:183], off
	v_add_co_u32_e32 v182, vcc, 0x4000, v182
	s_nop 1
	v_addc_co_u32_e32 v183, vcc, 0, v183, vcc
	global_load_dwordx4 v[210:213], v[182:183], off
	v_add_co_u32_e32 v182, vcc, 0x4000, v182
	s_nop 1
	v_addc_co_u32_e32 v183, vcc, 0, v183, vcc
	global_load_dwordx4 v[214:217], v[182:183], off
	v_add_co_u32_e32 v182, vcc, 0x4000, v182
	s_nop 1
	v_addc_co_u32_e32 v183, vcc, 0, v183, vcc
	global_load_dwordx4 v[218:221], v[182:183], off
	v_add_co_u32_e32 v182, vcc, 0x4000, v182
	s_nop 1
	v_addc_co_u32_e32 v183, vcc, 0, v183, vcc
	global_load_dwordx4 v[222:225], v[182:183], off
	v_add_co_u32_e32 v182, vcc, 0x4000, v182
	s_nop 1
	v_addc_co_u32_e32 v183, vcc, 0, v183, vcc
	global_load_dwordx4 v[226:229], v[182:183], off
	ds_write_b128 v104, v[32:35]
	ds_write_b128 v104, v[36:39] offset:32
	ds_write_b128 v104, v[40:43] offset:64
	ds_write_b128 v104, v[44:47] offset:96
	ds_write_b128 v104, v[48:51] offset:128
	ds_write_b128 v104, v[52:55] offset:160
	ds_write_b128 v104, v[56:59] offset:192
	ds_write_b128 v104, v[60:63] offset:224
	v_add_u32_e32 v32, 0xfffff020, v96
	v_xor_b32_e32 v32, s7, v32
	s_movk_i32 s4, 0x400
	v_cmp_gt_u32_e32 vcc, s4, v32
	s_and_b64 s[4:5], s[2:3], vcc
	v_cndmask_b32_e64 v38, 0, 1, s[4:5]
	s_movk_i32 s4, 0x1000
	v_cmp_gt_i32_e32 vcc, s4, v64
	s_nop 1
	v_cndmask_b32_e32 v32, v38, v102, vcc
	v_and_b32_e32 v32, 1, v32
	v_cmp_eq_u32_e32 vcc, 1, v32
	s_nop 1
	v_cndmask_b32_e64 v32, v171, 0, vcc
	v_add_u32_e32 v36, v103, v32
	ds_read_b128 v[32:35], v86
	ds_read_b128 v[40:43], v36
	s_and_b64 vcc, exec, s[0:1]
	s_waitcnt vmcnt(7) lgkmcnt(0)
	v_pk_fma_f32 v[34:35], v[34:35], v[42:43], v[200:201]
	v_pk_fma_f32 v[32:33], v[32:33], v[40:41], v[198:199]
	global_store_dwordx4 v[84:85], v[32:35], off
	s_cbranch_vccnz .LBB0_1471
	ds_read_b128 v[40:43], v36 offset:2048
	v_lshlrev_b64 v[36:37], 10, v[64:65]
	v_lshl_add_u64 v[36:37], v[36:37], 1, s[50:51]
	v_lshl_add_u64 v[36:37], v[98:99], 1, v[36:37]
	s_waitcnt lgkmcnt(0)
	v_pk_mul_f32 v[40:41], v[32:33], v[40:41]
	v_pk_mul_f32 v[32:33], v[32:33], v[32:33]
	v_pk_mul_f32 v[42:43], v[34:35], v[42:43]
	v_pk_mul_f32 v[34:35], v[34:35], v[34:35]
	v_add_f32_e32 v32, v32, v33
	v_add_f32_e32 v32, v34, v32
	v_add_f32_e32 v32, v35, v32
	v_cvt_pk_bf16_f32 v40, v40, v41
	v_cvt_pk_bf16_f32 v41, v42, v43
	v_add_f32_dpp v32, v32, v32 quad_perm:[1,0,3,2] row_mask:0xf bank_mask:0xf bound_ctrl:1
	global_store_dwordx2 v[36:37], v[40:41], off
	s_nop 0
	v_add_f32_dpp v32, v32, v32 quad_perm:[2,3,0,1] row_mask:0xf bank_mask:0xf bound_ctrl:1
	s_nop 1
	v_add_f32_dpp v32, v32, v32 row_half_mirror row_mask:0xf bank_mask:0xf bound_ctrl:1
	s_nop 1
	v_mov_b32_dpp v33, v32 row_mirror row_mask:0xf bank_mask:0xf bound_ctrl:1
	s_and_saveexec_b64 s[4:5], s[36:37]
	s_cbranch_execz .LBB0_1470
	v_ashrrev_i32_e32 v97, 31, v96
	v_lshl_add_u64 v[34:35], s[54:55], 0, v[68:69]
	v_lshl_add_u64 v[36:37], v[96:97], 0, v[128:129]
	v_lshl_add_u64 v[34:35], v[36:37], 2, v[34:35]
	v_add_f32_e32 v32, v32, v33
	global_store_dword v[34:35], v32, off offset:128

.LBB0_1471:
	v_or_b32_e32 v36, v66, v70
	v_ashrrev_i32_e32 v37, 31, v36
	v_lshlrev_b64 v[32:33], 12, v[36:37]
	v_lshl_add_u64 v[32:33], s[40:41], 0, v[32:33]
	v_lshl_add_u64 v[48:49], v[98:99], 2, v[32:33]
	s_movk_i32 s4, 0x1000
	v_cmp_gt_i32_e32 vcc, s4, v36
	s_nop 1
	v_cndmask_b32_e32 v39, v38, v102, vcc
	v_and_b32_e32 v39, 1, v39
	v_cmp_eq_u32_e32 vcc, 1, v39
	s_nop 1
	v_cndmask_b32_e64 v39, v171, 0, vcc
	v_add_u32_e32 v39, v103, v39
	ds_read_b128 v[40:43], v86 offset:1088
	ds_read_b128 v[44:47], v39
	s_and_b64 vcc, exec, s[0:1]
	s_waitcnt vmcnt(7) lgkmcnt(0)
	v_pk_fma_f32 v[34:35], v[42:43], v[46:47], v[204:205]
	v_pk_fma_f32 v[32:33], v[40:41], v[44:45], v[202:203]
	global_store_dwordx4 v[48:49], v[32:35], off
	s_cbranch_vccnz .LBB0_1475
	ds_read_b128 v[40:43], v39 offset:2048
	v_lshlrev_b64 v[36:37], 10, v[36:37]
	v_lshl_add_u64 v[36:37], v[36:37], 1, s[50:51]
	v_lshl_add_u64 v[36:37], v[98:99], 1, v[36:37]
	s_waitcnt lgkmcnt(0)
	v_pk_mul_f32 v[40:41], v[32:33], v[40:41]
	v_pk_mul_f32 v[32:33], v[32:33], v[32:33]
	v_pk_mul_f32 v[42:43], v[34:35], v[42:43]
	v_pk_mul_f32 v[34:35], v[34:35], v[34:35]
	v_add_f32_e32 v32, v32, v33
	v_add_f32_e32 v32, v34, v32
	v_add_f32_e32 v32, v35, v32
	v_cvt_pk_bf16_f32 v40, v40, v41
	v_cvt_pk_bf16_f32 v41, v42, v43
	v_add_f32_dpp v32, v32, v32 quad_perm:[1,0,3,2] row_mask:0xf bank_mask:0xf bound_ctrl:1
	global_store_dwordx2 v[36:37], v[40:41], off
	s_nop 0
	v_add_f32_dpp v32, v32, v32 quad_perm:[2,3,0,1] row_mask:0xf bank_mask:0xf bound_ctrl:1
	s_nop 1
	v_add_f32_dpp v32, v32, v32 row_half_mirror row_mask:0xf bank_mask:0xf bound_ctrl:1
	s_nop 1
	v_mov_b32_dpp v33, v32 row_mirror row_mask:0xf bank_mask:0xf bound_ctrl:1
	s_and_saveexec_b64 s[4:5], s[36:37]
	s_cbranch_execz .LBB0_1474
	v_mov_b32_e32 v71, v129
	v_ashrrev_i32_e32 v97, 31, v96
	v_lshl_add_u64 v[34:35], s[54:55], 0, v[68:69]
	v_lshl_add_u64 v[36:37], v[96:97], 0, v[70:71]
	v_lshl_add_u64 v[34:35], v[36:37], 2, v[34:35]
	v_add_f32_e32 v32, v32, v33
	global_store_dword v[34:35], v32, off offset:128

.LBB0_1475:
	v_or_b32_e32 v36, v66, v72
	v_ashrrev_i32_e32 v37, 31, v36
	v_lshlrev_b64 v[32:33], 12, v[36:37]
	v_lshl_add_u64 v[32:33], s[40:41], 0, v[32:33]
	v_lshl_add_u64 v[48:49], v[98:99], 2, v[32:33]
	s_movk_i32 s4, 0x1000
	v_cmp_gt_i32_e32 vcc, s4, v36
	s_nop 1
	v_cndmask_b32_e32 v39, v38, v102, vcc
	v_and_b32_e32 v39, 1, v39
	v_cmp_eq_u32_e32 vcc, 1, v39
	s_nop 1
	v_cndmask_b32_e64 v39, v171, 0, vcc
	v_add_u32_e32 v39, v103, v39
	ds_read_b128 v[40:43], v86 offset:2176
	ds_read_b128 v[44:47], v39
	s_and_b64 vcc, exec, s[0:1]
	s_waitcnt vmcnt(7) lgkmcnt(0)
	v_pk_fma_f32 v[34:35], v[42:43], v[46:47], v[208:209]
	v_pk_fma_f32 v[32:33], v[40:41], v[44:45], v[206:207]
	global_store_dwordx4 v[48:49], v[32:35], off
	s_cbranch_vccnz .LBB0_1479
	ds_read_b128 v[40:43], v39 offset:2048
	v_lshlrev_b64 v[36:37], 10, v[36:37]
	v_lshl_add_u64 v[36:37], v[36:37], 1, s[50:51]
	v_lshl_add_u64 v[36:37], v[98:99], 1, v[36:37]
	s_waitcnt lgkmcnt(0)
	v_pk_mul_f32 v[40:41], v[32:33], v[40:41]
	v_pk_mul_f32 v[32:33], v[32:33], v[32:33]
	v_pk_mul_f32 v[42:43], v[34:35], v[42:43]
	v_pk_mul_f32 v[34:35], v[34:35], v[34:35]
	v_add_f32_e32 v32, v32, v33
	v_add_f32_e32 v32, v34, v32
	v_add_f32_e32 v32, v35, v32
	v_cvt_pk_bf16_f32 v40, v40, v41
	v_cvt_pk_bf16_f32 v41, v42, v43
	v_add_f32_dpp v32, v32, v32 quad_perm:[1,0,3,2] row_mask:0xf bank_mask:0xf bound_ctrl:1
	global_store_dwordx2 v[36:37], v[40:41], off
	s_nop 0
	v_add_f32_dpp v32, v32, v32 quad_perm:[2,3,0,1] row_mask:0xf bank_mask:0xf bound_ctrl:1
	s_nop 1
	v_add_f32_dpp v32, v32, v32 row_half_mirror row_mask:0xf bank_mask:0xf bound_ctrl:1
	s_nop 1
	v_mov_b32_dpp v33, v32 row_mirror row_mask:0xf bank_mask:0xf bound_ctrl:1
	s_and_saveexec_b64 s[4:5], s[36:37]
	s_cbranch_execz .LBB0_1478
	v_mov_b32_e32 v73, v129
	v_ashrrev_i32_e32 v97, 31, v96
	v_lshl_add_u64 v[34:35], s[54:55], 0, v[68:69]
	v_lshl_add_u64 v[36:37], v[96:97], 0, v[72:73]
	v_lshl_add_u64 v[34:35], v[36:37], 2, v[34:35]
	v_add_f32_e32 v32, v32, v33
	global_store_dword v[34:35], v32, off offset:128

.LBB0_1479:
	v_or_b32_e32 v36, v66, v74
	v_ashrrev_i32_e32 v37, 31, v36
	v_lshlrev_b64 v[32:33], 12, v[36:37]
	v_lshl_add_u64 v[32:33], s[40:41], 0, v[32:33]
	v_lshl_add_u64 v[48:49], v[98:99], 2, v[32:33]
	s_movk_i32 s4, 0x1000
	v_cmp_gt_i32_e32 vcc, s4, v36
	s_nop 1
	v_cndmask_b32_e32 v39, v38, v102, vcc
	v_and_b32_e32 v39, 1, v39
	v_cmp_eq_u32_e32 vcc, 1, v39
	s_nop 1
	v_cndmask_b32_e64 v39, v171, 0, vcc
	v_add_u32_e32 v39, v103, v39
	ds_read_b128 v[40:43], v86 offset:3264
	ds_read_b128 v[44:47], v39
	s_and_b64 vcc, exec, s[0:1]
	s_waitcnt vmcnt(7) lgkmcnt(0)
	v_pk_fma_f32 v[34:35], v[42:43], v[46:47], v[212:213]
	v_pk_fma_f32 v[32:33], v[40:41], v[44:45], v[210:211]
	global_store_dwordx4 v[48:49], v[32:35], off
	s_cbranch_vccnz .LBB0_1483
	ds_read_b128 v[40:43], v39 offset:2048
	v_lshlrev_b64 v[36:37], 10, v[36:37]
	v_lshl_add_u64 v[36:37], v[36:37], 1, s[50:51]
	v_lshl_add_u64 v[36:37], v[98:99], 1, v[36:37]
	s_waitcnt lgkmcnt(0)
	v_pk_mul_f32 v[40:41], v[32:33], v[40:41]
	v_pk_mul_f32 v[32:33], v[32:33], v[32:33]
	v_pk_mul_f32 v[42:43], v[34:35], v[42:43]
	v_pk_mul_f32 v[34:35], v[34:35], v[34:35]
	v_add_f32_e32 v32, v32, v33
	v_add_f32_e32 v32, v34, v32
	v_add_f32_e32 v32, v35, v32
	v_cvt_pk_bf16_f32 v40, v40, v41
	v_cvt_pk_bf16_f32 v41, v42, v43
	v_add_f32_dpp v32, v32, v32 quad_perm:[1,0,3,2] row_mask:0xf bank_mask:0xf bound_ctrl:1
	global_store_dwordx2 v[36:37], v[40:41], off
	s_nop 0
	v_add_f32_dpp v32, v32, v32 quad_perm:[2,3,0,1] row_mask:0xf bank_mask:0xf bound_ctrl:1
	s_nop 1
	v_add_f32_dpp v32, v32, v32 row_half_mirror row_mask:0xf bank_mask:0xf bound_ctrl:1
	s_nop 1
	v_mov_b32_dpp v33, v32 row_mirror row_mask:0xf bank_mask:0xf bound_ctrl:1
	s_and_saveexec_b64 s[4:5], s[36:37]
	s_cbranch_execz .LBB0_1482
	v_mov_b32_e32 v75, v129
	v_ashrrev_i32_e32 v97, 31, v96
	v_lshl_add_u64 v[34:35], s[54:55], 0, v[68:69]
	v_lshl_add_u64 v[36:37], v[96:97], 0, v[74:75]
	v_lshl_add_u64 v[34:35], v[36:37], 2, v[34:35]
	v_add_f32_e32 v32, v32, v33
	global_store_dword v[34:35], v32, off offset:128

.LBB0_1483:
	v_or_b32_e32 v36, v66, v76
	v_ashrrev_i32_e32 v37, 31, v36
	v_lshlrev_b64 v[32:33], 12, v[36:37]
	v_lshl_add_u64 v[32:33], s[40:41], 0, v[32:33]
	v_lshl_add_u64 v[48:49], v[98:99], 2, v[32:33]
	s_movk_i32 s4, 0x1000
	v_cmp_gt_i32_e32 vcc, s4, v36
	s_nop 1
	v_cndmask_b32_e32 v39, v38, v102, vcc
	v_and_b32_e32 v39, 1, v39
	v_cmp_eq_u32_e32 vcc, 1, v39
	s_nop 1
	v_cndmask_b32_e64 v39, v171, 0, vcc
	v_add_u32_e32 v39, v103, v39
	ds_read_b128 v[40:43], v86 offset:4352
	ds_read_b128 v[44:47], v39
	s_and_b64 vcc, exec, s[0:1]
	s_waitcnt vmcnt(7) lgkmcnt(0)
	v_pk_fma_f32 v[34:35], v[42:43], v[46:47], v[216:217]
	v_pk_fma_f32 v[32:33], v[40:41], v[44:45], v[214:215]
	global_store_dwordx4 v[48:49], v[32:35], off
	s_cbranch_vccnz .LBB0_1487
	ds_read_b128 v[40:43], v39 offset:2048
	v_lshlrev_b64 v[36:37], 10, v[36:37]
	v_lshl_add_u64 v[36:37], v[36:37], 1, s[50:51]
	v_lshl_add_u64 v[36:37], v[98:99], 1, v[36:37]
	s_waitcnt lgkmcnt(0)
	v_pk_mul_f32 v[40:41], v[32:33], v[40:41]
	v_pk_mul_f32 v[32:33], v[32:33], v[32:33]
	v_pk_mul_f32 v[42:43], v[34:35], v[42:43]
	v_pk_mul_f32 v[34:35], v[34:35], v[34:35]
	v_add_f32_e32 v32, v32, v33
	v_add_f32_e32 v32, v34, v32
	v_add_f32_e32 v32, v35, v32
	v_cvt_pk_bf16_f32 v40, v40, v41
	v_cvt_pk_bf16_f32 v41, v42, v43
	v_add_f32_dpp v32, v32, v32 quad_perm:[1,0,3,2] row_mask:0xf bank_mask:0xf bound_ctrl:1
	global_store_dwordx2 v[36:37], v[40:41], off
	s_nop 0
	v_add_f32_dpp v32, v32, v32 quad_perm:[2,3,0,1] row_mask:0xf bank_mask:0xf bound_ctrl:1
	s_nop 1
	v_add_f32_dpp v32, v32, v32 row_half_mirror row_mask:0xf bank_mask:0xf bound_ctrl:1
	s_nop 1
	v_mov_b32_dpp v33, v32 row_mirror row_mask:0xf bank_mask:0xf bound_ctrl:1
	s_and_saveexec_b64 s[4:5], s[36:37]
	s_cbranch_execz .LBB0_1486
	v_mov_b32_e32 v77, v129
	v_ashrrev_i32_e32 v97, 31, v96
	v_lshl_add_u64 v[34:35], s[54:55], 0, v[68:69]
	v_lshl_add_u64 v[36:37], v[96:97], 0, v[76:77]
	v_lshl_add_u64 v[34:35], v[36:37], 2, v[34:35]
	v_add_f32_e32 v32, v32, v33
	global_store_dword v[34:35], v32, off offset:128

.LBB0_1487:
	v_or_b32_e32 v36, v66, v78
	v_ashrrev_i32_e32 v37, 31, v36
	v_lshlrev_b64 v[32:33], 12, v[36:37]
	v_lshl_add_u64 v[32:33], s[40:41], 0, v[32:33]
	v_lshl_add_u64 v[48:49], v[98:99], 2, v[32:33]
	s_movk_i32 s4, 0x1000
	v_cmp_gt_i32_e32 vcc, s4, v36
	s_nop 1
	v_cndmask_b32_e32 v39, v38, v102, vcc
	v_and_b32_e32 v39, 1, v39
	v_cmp_eq_u32_e32 vcc, 1, v39
	s_nop 1
	v_cndmask_b32_e64 v39, v171, 0, vcc
	v_add_u32_e32 v39, v103, v39
	ds_read_b128 v[40:43], v86 offset:5440
	ds_read_b128 v[44:47], v39
	s_and_b64 vcc, exec, s[0:1]
	s_waitcnt vmcnt(7) lgkmcnt(0)
	v_pk_fma_f32 v[34:35], v[42:43], v[46:47], v[220:221]
	v_pk_fma_f32 v[32:33], v[40:41], v[44:45], v[218:219]
	global_store_dwordx4 v[48:49], v[32:35], off
	s_cbranch_vccnz .LBB0_1491
	ds_read_b128 v[40:43], v39 offset:2048
	v_lshlrev_b64 v[36:37], 10, v[36:37]
	v_lshl_add_u64 v[36:37], v[36:37], 1, s[50:51]
	v_lshl_add_u64 v[36:37], v[98:99], 1, v[36:37]
	s_waitcnt lgkmcnt(0)
	v_pk_mul_f32 v[40:41], v[32:33], v[40:41]
	v_pk_mul_f32 v[32:33], v[32:33], v[32:33]
	v_pk_mul_f32 v[42:43], v[34:35], v[42:43]
	v_pk_mul_f32 v[34:35], v[34:35], v[34:35]
	v_add_f32_e32 v32, v32, v33
	v_add_f32_e32 v32, v34, v32
	v_add_f32_e32 v32, v35, v32
	v_cvt_pk_bf16_f32 v40, v40, v41
	v_cvt_pk_bf16_f32 v41, v42, v43
	v_add_f32_dpp v32, v32, v32 quad_perm:[1,0,3,2] row_mask:0xf bank_mask:0xf bound_ctrl:1
	global_store_dwordx2 v[36:37], v[40:41], off
	s_nop 0
	v_add_f32_dpp v32, v32, v32 quad_perm:[2,3,0,1] row_mask:0xf bank_mask:0xf bound_ctrl:1
	s_nop 1
	v_add_f32_dpp v32, v32, v32 row_half_mirror row_mask:0xf bank_mask:0xf bound_ctrl:1
	s_nop 1
	v_mov_b32_dpp v33, v32 row_mirror row_mask:0xf bank_mask:0xf bound_ctrl:1
	s_and_saveexec_b64 s[4:5], s[36:37]
	s_cbranch_execz .LBB0_1490
	v_mov_b32_e32 v79, v129
	v_ashrrev_i32_e32 v97, 31, v96
	v_lshl_add_u64 v[34:35], s[54:55], 0, v[68:69]
	v_lshl_add_u64 v[36:37], v[96:97], 0, v[78:79]
	v_lshl_add_u64 v[34:35], v[36:37], 2, v[34:35]
	v_add_f32_e32 v32, v32, v33
	global_store_dword v[34:35], v32, off offset:128

.LBB0_1491:
	v_or_b32_e32 v36, v66, v80
	v_ashrrev_i32_e32 v37, 31, v36
	v_lshlrev_b64 v[32:33], 12, v[36:37]
	v_lshl_add_u64 v[32:33], s[40:41], 0, v[32:33]
	v_lshl_add_u64 v[48:49], v[98:99], 2, v[32:33]
	s_movk_i32 s4, 0x1000
	v_cmp_gt_i32_e32 vcc, s4, v36
	s_nop 1
	v_cndmask_b32_e32 v39, v38, v102, vcc
	v_and_b32_e32 v39, 1, v39
	v_cmp_eq_u32_e32 vcc, 1, v39
	s_nop 1
	v_cndmask_b32_e64 v39, v171, 0, vcc
	v_add_u32_e32 v39, v103, v39
	ds_read_b128 v[40:43], v86 offset:6528
	ds_read_b128 v[44:47], v39
	s_and_b64 vcc, exec, s[0:1]
	s_waitcnt vmcnt(7) lgkmcnt(0)
	v_pk_fma_f32 v[34:35], v[42:43], v[46:47], v[224:225]
	v_pk_fma_f32 v[32:33], v[40:41], v[44:45], v[222:223]
	global_store_dwordx4 v[48:49], v[32:35], off
	s_cbranch_vccnz .LBB0_1495
	ds_read_b128 v[40:43], v39 offset:2048
	v_lshlrev_b64 v[36:37], 10, v[36:37]
	v_lshl_add_u64 v[36:37], v[36:37], 1, s[50:51]
	v_lshl_add_u64 v[36:37], v[98:99], 1, v[36:37]
	s_waitcnt lgkmcnt(0)
	v_pk_mul_f32 v[40:41], v[32:33], v[40:41]
	v_pk_mul_f32 v[32:33], v[32:33], v[32:33]
	v_pk_mul_f32 v[42:43], v[34:35], v[42:43]
	v_pk_mul_f32 v[34:35], v[34:35], v[34:35]
	v_add_f32_e32 v32, v32, v33
	v_add_f32_e32 v32, v34, v32
	v_add_f32_e32 v32, v35, v32
	v_cvt_pk_bf16_f32 v40, v40, v41
	v_cvt_pk_bf16_f32 v41, v42, v43
	v_add_f32_dpp v32, v32, v32 quad_perm:[1,0,3,2] row_mask:0xf bank_mask:0xf bound_ctrl:1
	global_store_dwordx2 v[36:37], v[40:41], off
	s_nop 0
	v_add_f32_dpp v32, v32, v32 quad_perm:[2,3,0,1] row_mask:0xf bank_mask:0xf bound_ctrl:1
	s_nop 1
	v_add_f32_dpp v32, v32, v32 row_half_mirror row_mask:0xf bank_mask:0xf bound_ctrl:1
	s_nop 1
	v_mov_b32_dpp v33, v32 row_mirror row_mask:0xf bank_mask:0xf bound_ctrl:1
	s_and_saveexec_b64 s[4:5], s[36:37]
	s_cbranch_execz .LBB0_1494
	v_mov_b32_e32 v81, v129
	v_ashrrev_i32_e32 v97, 31, v96
	v_lshl_add_u64 v[34:35], s[54:55], 0, v[68:69]
	v_lshl_add_u64 v[36:37], v[96:97], 0, v[80:81]
	v_lshl_add_u64 v[34:35], v[36:37], 2, v[34:35]
	v_add_f32_e32 v32, v32, v33
	global_store_dword v[34:35], v32, off offset:128

.LBB0_1495:
	v_or_b32_e32 v36, v66, v82
	v_ashrrev_i32_e32 v37, 31, v36
	v_lshlrev_b64 v[32:33], 12, v[36:37]
	v_lshl_add_u64 v[32:33], s[40:41], 0, v[32:33]
	v_lshl_add_u64 v[48:49], v[98:99], 2, v[32:33]
	s_movk_i32 s4, 0x1000
	v_cmp_gt_i32_e32 vcc, s4, v36
	s_nop 1
	v_cndmask_b32_e32 v38, v38, v102, vcc
	v_and_b32_e32 v38, 1, v38
	v_cmp_eq_u32_e32 vcc, 1, v38
	s_nop 1
	v_cndmask_b32_e64 v38, v171, 0, vcc
	v_add_u32_e32 v38, v103, v38
	ds_read_b128 v[40:43], v86 offset:7616
	ds_read_b128 v[44:47], v38
	s_and_b64 vcc, exec, s[0:1]
	s_waitcnt vmcnt(7) lgkmcnt(0)
	v_pk_fma_f32 v[34:35], v[42:43], v[46:47], v[228:229]
	v_pk_fma_f32 v[32:33], v[40:41], v[44:45], v[226:227]
	global_store_dwordx4 v[48:49], v[32:35], off
	s_cbranch_vccnz .LBB0_1499
	ds_read_b128 v[38:41], v38 offset:2048
	v_lshlrev_b64 v[36:37], 10, v[36:37]
	v_lshl_add_u64 v[36:37], v[36:37], 1, s[50:51]
	v_lshl_add_u64 v[36:37], v[98:99], 1, v[36:37]
	s_waitcnt lgkmcnt(0)
	v_pk_mul_f32 v[38:39], v[32:33], v[38:39]
	v_pk_mul_f32 v[32:33], v[32:33], v[32:33]
	v_pk_mul_f32 v[40:41], v[34:35], v[40:41]
	v_pk_mul_f32 v[34:35], v[34:35], v[34:35]
	v_add_f32_e32 v32, v32, v33
	v_add_f32_e32 v32, v34, v32
	v_add_f32_e32 v32, v35, v32
	v_cvt_pk_bf16_f32 v38, v38, v39
	v_cvt_pk_bf16_f32 v39, v40, v41
	v_add_f32_dpp v32, v32, v32 quad_perm:[1,0,3,2] row_mask:0xf bank_mask:0xf bound_ctrl:1
	global_store_dwordx2 v[36:37], v[38:39], off
	s_nop 0
	v_add_f32_dpp v32, v32, v32 quad_perm:[2,3,0,1] row_mask:0xf bank_mask:0xf bound_ctrl:1
	s_nop 1
	v_add_f32_dpp v32, v32, v32 row_half_mirror row_mask:0xf bank_mask:0xf bound_ctrl:1
	s_nop 1
	v_mov_b32_dpp v33, v32 row_mirror row_mask:0xf bank_mask:0xf bound_ctrl:1
	s_and_saveexec_b64 s[4:5], s[36:37]
	s_cbranch_execz .LBB0_1498
	v_mov_b32_e32 v83, v129
	v_ashrrev_i32_e32 v97, 31, v96
	v_lshl_add_u64 v[34:35], s[54:55], 0, v[68:69]
	v_lshl_add_u64 v[36:37], v[96:97], 0, v[82:83]
	v_lshl_add_u64 v[34:35], v[36:37], 2, v[34:35]
	v_add_f32_e32 v32, v32, v33
	global_store_dword v[34:35], v32, off offset:128

.LBB0_1499:
	s_nop 0
	v_add_u32_e32 v34, 64, v96
	v_or_b32_e32 v32, v34, v128
	v_ashrrev_i32_e32 v33, 31, v32
	v_lshlrev_b64 v[36:37], 12, v[32:33]
	v_lshl_add_u64 v[36:37], s[40:41], 0, v[36:37]
	v_lshl_add_u64 v[40:41], v[98:99], 2, v[36:37]
	global_load_dwordx4 v[198:201], v[40:41], off
	v_add_co_u32_e32 v182, vcc, 0x4000, v40
	s_nop 1
	v_addc_co_u32_e32 v183, vcc, 0, v41, vcc
	global_load_dwordx4 v[202:205], v[182:183], off
	v_add_co_u32_e32 v182, vcc, 0x4000, v182
	s_nop 1
	v_addc_co_u32_e32 v183, vcc, 0, v183, vcc
	global_load_dwordx4 v[206:209], v[182:183], off
	v_add_co_u32_e32 v182, vcc, 0x4000, v182
	s_nop 1
	v_addc_co_u32_e32 v183, vcc, 0, v183, vcc
	global_load_dwordx4 v[210:213], v[182:183], off
	v_add_co_u32_e32 v182, vcc, 0x4000, v182
	s_nop 1
	v_addc_co_u32_e32 v183, vcc, 0, v183, vcc
	global_load_dwordx4 v[214:217], v[182:183], off
	v_add_co_u32_e32 v182, vcc, 0x4000, v182
	s_nop 1
	v_addc_co_u32_e32 v183, vcc, 0, v183, vcc
	global_load_dwordx4 v[218:221], v[182:183], off
	v_add_co_u32_e32 v182, vcc, 0x4000, v182
	s_nop 1
	v_addc_co_u32_e32 v183, vcc, 0, v183, vcc
	global_load_dwordx4 v[222:225], v[182:183], off
	v_add_co_u32_e32 v182, vcc, 0x4000, v182
	s_nop 1
	v_addc_co_u32_e32 v183, vcc, 0, v183, vcc
	global_load_dwordx4 v[226:229], v[182:183], off
	ds_write_b128 v104, v[0:3]
	ds_write_b128 v104, v[4:7] offset:32
	ds_write_b128 v104, v[8:11] offset:64
	ds_write_b128 v104, v[12:15] offset:96
	ds_write_b128 v104, v[16:19] offset:128
	ds_write_b128 v104, v[20:23] offset:160
	ds_write_b128 v104, v[24:27] offset:192
	ds_write_b128 v104, v[28:31] offset:224
	v_add_u32_e32 v0, 0xfffff040, v96
	v_xor_b32_e32 v0, s7, v0
	s_movk_i32 s4, 0x400
	v_cmp_gt_u32_e32 vcc, s4, v0
	s_and_b64 s[2:3], s[2:3], vcc
	v_cndmask_b32_e64 v6, 0, 1, s[2:3]
	s_movk_i32 s2, 0x1000
	v_cmp_gt_i32_e32 vcc, s2, v32
	s_nop 1
	v_cndmask_b32_e32 v0, v6, v102, vcc
	v_and_b32_e32 v0, 1, v0
	v_cmp_eq_u32_e32 vcc, 1, v0
	s_nop 1
	v_cndmask_b32_e64 v0, v171, 0, vcc
	v_add_u32_e32 v4, v103, v0
	ds_read_b128 v[0:3], v86
	ds_read_b128 v[8:11], v4
	s_and_b64 vcc, exec, s[0:1]
	s_waitcnt vmcnt(7) lgkmcnt(0)
	v_pk_fma_f32 v[2:3], v[2:3], v[10:11], v[200:201]
	v_pk_fma_f32 v[0:1], v[0:1], v[8:9], v[198:199]
	global_store_dwordx4 v[40:41], v[0:3], off
	s_cbranch_vccnz .LBB0_1503
	ds_read_b128 v[8:11], v4 offset:2048
	v_lshlrev_b64 v[4:5], 10, v[32:33]
	v_lshl_add_u64 v[4:5], v[4:5], 1, s[50:51]
	v_lshl_add_u64 v[4:5], v[98:99], 1, v[4:5]
	s_waitcnt lgkmcnt(0)
	v_pk_mul_f32 v[8:9], v[0:1], v[8:9]
	v_pk_mul_f32 v[0:1], v[0:1], v[0:1]
	v_pk_mul_f32 v[10:11], v[2:3], v[10:11]
	v_pk_mul_f32 v[2:3], v[2:3], v[2:3]
	v_add_f32_e32 v0, v0, v1
	v_add_f32_e32 v0, v2, v0
	v_add_f32_e32 v0, v3, v0
	v_cvt_pk_bf16_f32 v8, v8, v9
	v_cvt_pk_bf16_f32 v9, v10, v11
	v_add_f32_dpp v0, v0, v0 quad_perm:[1,0,3,2] row_mask:0xf bank_mask:0xf bound_ctrl:1
	global_store_dwordx2 v[4:5], v[8:9], off
	s_nop 0
	v_add_f32_dpp v0, v0, v0 quad_perm:[2,3,0,1] row_mask:0xf bank_mask:0xf bound_ctrl:1
	s_nop 1
	v_add_f32_dpp v0, v0, v0 row_half_mirror row_mask:0xf bank_mask:0xf bound_ctrl:1
	s_nop 1
	v_mov_b32_dpp v1, v0 row_mirror row_mask:0xf bank_mask:0xf bound_ctrl:1
	s_and_saveexec_b64 s[2:3], s[36:37]
	s_cbranch_execz .LBB0_1502
	v_ashrrev_i32_e32 v97, 31, v96
	v_lshl_add_u64 v[2:3], s[54:55], 0, v[68:69]
	v_lshl_add_u64 v[4:5], v[96:97], 0, v[128:129]
	v_lshl_add_u64 v[2:3], v[4:5], 2, v[2:3]
	v_add_f32_e32 v0, v0, v1
	global_store_dword v[2:3], v0, off offset:256

.LBB0_1503:
	v_or_b32_e32 v4, v34, v70
	v_ashrrev_i32_e32 v5, 31, v4
	v_lshlrev_b64 v[0:1], 12, v[4:5]
	v_lshl_add_u64 v[0:1], s[40:41], 0, v[0:1]
	v_lshl_add_u64 v[16:17], v[98:99], 2, v[0:1]
	s_movk_i32 s2, 0x1000
	v_cmp_gt_i32_e32 vcc, s2, v4
	s_nop 1
	v_cndmask_b32_e32 v7, v6, v102, vcc
	v_and_b32_e32 v7, 1, v7
	v_cmp_eq_u32_e32 vcc, 1, v7
	s_nop 1
	v_cndmask_b32_e64 v7, v171, 0, vcc
	v_add_u32_e32 v7, v103, v7
	ds_read_b128 v[8:11], v86 offset:1088
	ds_read_b128 v[12:15], v7
	s_and_b64 vcc, exec, s[0:1]
	s_waitcnt vmcnt(7) lgkmcnt(0)
	v_pk_fma_f32 v[2:3], v[10:11], v[14:15], v[204:205]
	v_pk_fma_f32 v[0:1], v[8:9], v[12:13], v[202:203]
	global_store_dwordx4 v[16:17], v[0:3], off
	s_cbranch_vccnz .LBB0_1507
	ds_read_b128 v[8:11], v7 offset:2048
	v_lshlrev_b64 v[4:5], 10, v[4:5]
	v_lshl_add_u64 v[4:5], v[4:5], 1, s[50:51]
	v_lshl_add_u64 v[4:5], v[98:99], 1, v[4:5]
	s_waitcnt lgkmcnt(0)
	v_pk_mul_f32 v[8:9], v[0:1], v[8:9]
	v_pk_mul_f32 v[0:1], v[0:1], v[0:1]
	v_pk_mul_f32 v[10:11], v[2:3], v[10:11]
	v_pk_mul_f32 v[2:3], v[2:3], v[2:3]
	v_add_f32_e32 v0, v0, v1
	v_add_f32_e32 v0, v2, v0
	v_add_f32_e32 v0, v3, v0
	v_cvt_pk_bf16_f32 v8, v8, v9
	v_cvt_pk_bf16_f32 v9, v10, v11
	v_add_f32_dpp v0, v0, v0 quad_perm:[1,0,3,2] row_mask:0xf bank_mask:0xf bound_ctrl:1
	global_store_dwordx2 v[4:5], v[8:9], off
	s_nop 0
	v_add_f32_dpp v0, v0, v0 quad_perm:[2,3,0,1] row_mask:0xf bank_mask:0xf bound_ctrl:1
	s_nop 1
	v_add_f32_dpp v0, v0, v0 row_half_mirror row_mask:0xf bank_mask:0xf bound_ctrl:1
	s_nop 1
	v_mov_b32_dpp v1, v0 row_mirror row_mask:0xf bank_mask:0xf bound_ctrl:1
	s_and_saveexec_b64 s[2:3], s[36:37]
	s_cbranch_execz .LBB0_1506
	v_mov_b32_e32 v71, v129
	v_ashrrev_i32_e32 v97, 31, v96
	v_lshl_add_u64 v[2:3], s[54:55], 0, v[68:69]
	v_lshl_add_u64 v[4:5], v[96:97], 0, v[70:71]
	v_lshl_add_u64 v[2:3], v[4:5], 2, v[2:3]
	v_add_f32_e32 v0, v0, v1
	global_store_dword v[2:3], v0, off offset:256

.LBB0_1507:
	v_or_b32_e32 v4, v34, v72
	v_ashrrev_i32_e32 v5, 31, v4
	v_lshlrev_b64 v[0:1], 12, v[4:5]
	v_lshl_add_u64 v[0:1], s[40:41], 0, v[0:1]
	v_lshl_add_u64 v[16:17], v[98:99], 2, v[0:1]
	s_movk_i32 s2, 0x1000
	v_cmp_gt_i32_e32 vcc, s2, v4
	s_nop 1
	v_cndmask_b32_e32 v7, v6, v102, vcc
	v_and_b32_e32 v7, 1, v7
	v_cmp_eq_u32_e32 vcc, 1, v7
	s_nop 1
	v_cndmask_b32_e64 v7, v171, 0, vcc
	v_add_u32_e32 v7, v103, v7
	ds_read_b128 v[8:11], v86 offset:2176
	ds_read_b128 v[12:15], v7
	s_and_b64 vcc, exec, s[0:1]
	s_waitcnt vmcnt(7) lgkmcnt(0)
	v_pk_fma_f32 v[2:3], v[10:11], v[14:15], v[208:209]
	v_pk_fma_f32 v[0:1], v[8:9], v[12:13], v[206:207]
	global_store_dwordx4 v[16:17], v[0:3], off
	s_cbranch_vccnz .LBB0_1511
	ds_read_b128 v[8:11], v7 offset:2048
	v_lshlrev_b64 v[4:5], 10, v[4:5]
	v_lshl_add_u64 v[4:5], v[4:5], 1, s[50:51]
	v_lshl_add_u64 v[4:5], v[98:99], 1, v[4:5]
	s_waitcnt lgkmcnt(0)
	v_pk_mul_f32 v[8:9], v[0:1], v[8:9]
	v_pk_mul_f32 v[0:1], v[0:1], v[0:1]
	v_pk_mul_f32 v[10:11], v[2:3], v[10:11]
	v_pk_mul_f32 v[2:3], v[2:3], v[2:3]
	v_add_f32_e32 v0, v0, v1
	v_add_f32_e32 v0, v2, v0
	v_add_f32_e32 v0, v3, v0
	v_cvt_pk_bf16_f32 v8, v8, v9
	v_cvt_pk_bf16_f32 v9, v10, v11
	v_add_f32_dpp v0, v0, v0 quad_perm:[1,0,3,2] row_mask:0xf bank_mask:0xf bound_ctrl:1
	global_store_dwordx2 v[4:5], v[8:9], off
	s_nop 0
	v_add_f32_dpp v0, v0, v0 quad_perm:[2,3,0,1] row_mask:0xf bank_mask:0xf bound_ctrl:1
	s_nop 1
	v_add_f32_dpp v0, v0, v0 row_half_mirror row_mask:0xf bank_mask:0xf bound_ctrl:1
	s_nop 1
	v_mov_b32_dpp v1, v0 row_mirror row_mask:0xf bank_mask:0xf bound_ctrl:1
	s_and_saveexec_b64 s[2:3], s[36:37]
	s_cbranch_execz .LBB0_1510
	v_mov_b32_e32 v73, v129
	v_ashrrev_i32_e32 v97, 31, v96
	v_lshl_add_u64 v[2:3], s[54:55], 0, v[68:69]
	v_lshl_add_u64 v[4:5], v[96:97], 0, v[72:73]
	v_lshl_add_u64 v[2:3], v[4:5], 2, v[2:3]
	v_add_f32_e32 v0, v0, v1
	global_store_dword v[2:3], v0, off offset:256

.LBB0_1511:
	v_or_b32_e32 v4, v34, v74
	v_ashrrev_i32_e32 v5, 31, v4
	v_lshlrev_b64 v[0:1], 12, v[4:5]
	v_lshl_add_u64 v[0:1], s[40:41], 0, v[0:1]
	v_lshl_add_u64 v[16:17], v[98:99], 2, v[0:1]
	s_movk_i32 s2, 0x1000
	v_cmp_gt_i32_e32 vcc, s2, v4
	s_nop 1
	v_cndmask_b32_e32 v7, v6, v102, vcc
	v_and_b32_e32 v7, 1, v7
	v_cmp_eq_u32_e32 vcc, 1, v7
	s_nop 1
	v_cndmask_b32_e64 v7, v171, 0, vcc
	v_add_u32_e32 v7, v103, v7
	ds_read_b128 v[8:11], v86 offset:3264
	ds_read_b128 v[12:15], v7
	s_and_b64 vcc, exec, s[0:1]
	s_waitcnt vmcnt(7) lgkmcnt(0)
	v_pk_fma_f32 v[2:3], v[10:11], v[14:15], v[212:213]
	v_pk_fma_f32 v[0:1], v[8:9], v[12:13], v[210:211]
	global_store_dwordx4 v[16:17], v[0:3], off
	s_cbranch_vccnz .LBB0_1515
	ds_read_b128 v[8:11], v7 offset:2048
	v_lshlrev_b64 v[4:5], 10, v[4:5]
	v_lshl_add_u64 v[4:5], v[4:5], 1, s[50:51]
	v_lshl_add_u64 v[4:5], v[98:99], 1, v[4:5]
	s_waitcnt lgkmcnt(0)
	v_pk_mul_f32 v[8:9], v[0:1], v[8:9]
	v_pk_mul_f32 v[0:1], v[0:1], v[0:1]
	v_pk_mul_f32 v[10:11], v[2:3], v[10:11]
	v_pk_mul_f32 v[2:3], v[2:3], v[2:3]
	v_add_f32_e32 v0, v0, v1
	v_add_f32_e32 v0, v2, v0
	v_add_f32_e32 v0, v3, v0
	v_cvt_pk_bf16_f32 v8, v8, v9
	v_cvt_pk_bf16_f32 v9, v10, v11
	v_add_f32_dpp v0, v0, v0 quad_perm:[1,0,3,2] row_mask:0xf bank_mask:0xf bound_ctrl:1
	global_store_dwordx2 v[4:5], v[8:9], off
	s_nop 0
	v_add_f32_dpp v0, v0, v0 quad_perm:[2,3,0,1] row_mask:0xf bank_mask:0xf bound_ctrl:1
	s_nop 1
	v_add_f32_dpp v0, v0, v0 row_half_mirror row_mask:0xf bank_mask:0xf bound_ctrl:1
	s_nop 1
	v_mov_b32_dpp v1, v0 row_mirror row_mask:0xf bank_mask:0xf bound_ctrl:1
	s_and_saveexec_b64 s[2:3], s[36:37]
	s_cbranch_execz .LBB0_1514
	v_mov_b32_e32 v75, v129
	v_ashrrev_i32_e32 v97, 31, v96
	v_lshl_add_u64 v[2:3], s[54:55], 0, v[68:69]
	v_lshl_add_u64 v[4:5], v[96:97], 0, v[74:75]
	v_lshl_add_u64 v[2:3], v[4:5], 2, v[2:3]
	v_add_f32_e32 v0, v0, v1
	global_store_dword v[2:3], v0, off offset:256

.LBB0_1515:
	v_or_b32_e32 v4, v34, v76
	v_ashrrev_i32_e32 v5, 31, v4
	v_lshlrev_b64 v[0:1], 12, v[4:5]
	v_lshl_add_u64 v[0:1], s[40:41], 0, v[0:1]
	v_lshl_add_u64 v[16:17], v[98:99], 2, v[0:1]
	s_movk_i32 s2, 0x1000
	v_cmp_gt_i32_e32 vcc, s2, v4
	s_nop 1
	v_cndmask_b32_e32 v7, v6, v102, vcc
	v_and_b32_e32 v7, 1, v7
	v_cmp_eq_u32_e32 vcc, 1, v7
	s_nop 1
	v_cndmask_b32_e64 v7, v171, 0, vcc
	v_add_u32_e32 v7, v103, v7
	ds_read_b128 v[8:11], v86 offset:4352
	ds_read_b128 v[12:15], v7
	s_and_b64 vcc, exec, s[0:1]
	s_waitcnt vmcnt(7) lgkmcnt(0)
	v_pk_fma_f32 v[2:3], v[10:11], v[14:15], v[216:217]
	v_pk_fma_f32 v[0:1], v[8:9], v[12:13], v[214:215]
	global_store_dwordx4 v[16:17], v[0:3], off
	s_cbranch_vccnz .LBB0_1519
	ds_read_b128 v[8:11], v7 offset:2048
	v_lshlrev_b64 v[4:5], 10, v[4:5]
	v_lshl_add_u64 v[4:5], v[4:5], 1, s[50:51]
	v_lshl_add_u64 v[4:5], v[98:99], 1, v[4:5]
	s_waitcnt lgkmcnt(0)
	v_pk_mul_f32 v[8:9], v[0:1], v[8:9]
	v_pk_mul_f32 v[0:1], v[0:1], v[0:1]
	v_pk_mul_f32 v[10:11], v[2:3], v[10:11]
	v_pk_mul_f32 v[2:3], v[2:3], v[2:3]
	v_add_f32_e32 v0, v0, v1
	v_add_f32_e32 v0, v2, v0
	v_add_f32_e32 v0, v3, v0
	v_cvt_pk_bf16_f32 v8, v8, v9
	v_cvt_pk_bf16_f32 v9, v10, v11
	v_add_f32_dpp v0, v0, v0 quad_perm:[1,0,3,2] row_mask:0xf bank_mask:0xf bound_ctrl:1
	global_store_dwordx2 v[4:5], v[8:9], off
	s_nop 0
	v_add_f32_dpp v0, v0, v0 quad_perm:[2,3,0,1] row_mask:0xf bank_mask:0xf bound_ctrl:1
	s_nop 1
	v_add_f32_dpp v0, v0, v0 row_half_mirror row_mask:0xf bank_mask:0xf bound_ctrl:1
	s_nop 1
	v_mov_b32_dpp v1, v0 row_mirror row_mask:0xf bank_mask:0xf bound_ctrl:1
	s_and_saveexec_b64 s[2:3], s[36:37]
	s_cbranch_execz .LBB0_1518
	v_mov_b32_e32 v77, v129
	v_ashrrev_i32_e32 v97, 31, v96
	v_lshl_add_u64 v[2:3], s[54:55], 0, v[68:69]
	v_lshl_add_u64 v[4:5], v[96:97], 0, v[76:77]
	v_lshl_add_u64 v[2:3], v[4:5], 2, v[2:3]
	v_add_f32_e32 v0, v0, v1
	global_store_dword v[2:3], v0, off offset:256

.LBB0_1519:
	v_or_b32_e32 v4, v34, v78
	v_ashrrev_i32_e32 v5, 31, v4
	v_lshlrev_b64 v[0:1], 12, v[4:5]
	v_lshl_add_u64 v[0:1], s[40:41], 0, v[0:1]
	v_lshl_add_u64 v[16:17], v[98:99], 2, v[0:1]
	s_movk_i32 s2, 0x1000
	v_cmp_gt_i32_e32 vcc, s2, v4
	s_nop 1
	v_cndmask_b32_e32 v7, v6, v102, vcc
	v_and_b32_e32 v7, 1, v7
	v_cmp_eq_u32_e32 vcc, 1, v7
	s_nop 1
	v_cndmask_b32_e64 v7, v171, 0, vcc
	v_add_u32_e32 v7, v103, v7
	ds_read_b128 v[8:11], v86 offset:5440
	ds_read_b128 v[12:15], v7
	s_and_b64 vcc, exec, s[0:1]
	s_waitcnt vmcnt(7) lgkmcnt(0)
	v_pk_fma_f32 v[2:3], v[10:11], v[14:15], v[220:221]
	v_pk_fma_f32 v[0:1], v[8:9], v[12:13], v[218:219]
	global_store_dwordx4 v[16:17], v[0:3], off
	s_cbranch_vccnz .LBB0_1523
	ds_read_b128 v[8:11], v7 offset:2048
	v_lshlrev_b64 v[4:5], 10, v[4:5]
	v_lshl_add_u64 v[4:5], v[4:5], 1, s[50:51]
	v_lshl_add_u64 v[4:5], v[98:99], 1, v[4:5]
	s_waitcnt lgkmcnt(0)
	v_pk_mul_f32 v[8:9], v[0:1], v[8:9]
	v_pk_mul_f32 v[0:1], v[0:1], v[0:1]
	v_pk_mul_f32 v[10:11], v[2:3], v[10:11]
	v_pk_mul_f32 v[2:3], v[2:3], v[2:3]
	v_add_f32_e32 v0, v0, v1
	v_add_f32_e32 v0, v2, v0
	v_add_f32_e32 v0, v3, v0
	v_cvt_pk_bf16_f32 v8, v8, v9
	v_cvt_pk_bf16_f32 v9, v10, v11
	v_add_f32_dpp v0, v0, v0 quad_perm:[1,0,3,2] row_mask:0xf bank_mask:0xf bound_ctrl:1
	global_store_dwordx2 v[4:5], v[8:9], off
	s_nop 0
	v_add_f32_dpp v0, v0, v0 quad_perm:[2,3,0,1] row_mask:0xf bank_mask:0xf bound_ctrl:1
	s_nop 1
	v_add_f32_dpp v0, v0, v0 row_half_mirror row_mask:0xf bank_mask:0xf bound_ctrl:1
	s_nop 1
	v_mov_b32_dpp v1, v0 row_mirror row_mask:0xf bank_mask:0xf bound_ctrl:1
	s_and_saveexec_b64 s[2:3], s[36:37]
	s_cbranch_execz .LBB0_1522
	v_mov_b32_e32 v79, v129
	v_ashrrev_i32_e32 v97, 31, v96
	v_lshl_add_u64 v[2:3], s[54:55], 0, v[68:69]
	v_lshl_add_u64 v[4:5], v[96:97], 0, v[78:79]
	v_lshl_add_u64 v[2:3], v[4:5], 2, v[2:3]
	v_add_f32_e32 v0, v0, v1
	global_store_dword v[2:3], v0, off offset:256

.LBB0_1523:
	v_or_b32_e32 v4, v34, v80
	v_ashrrev_i32_e32 v5, 31, v4
	v_lshlrev_b64 v[0:1], 12, v[4:5]
	v_lshl_add_u64 v[0:1], s[40:41], 0, v[0:1]
	v_lshl_add_u64 v[16:17], v[98:99], 2, v[0:1]
	s_movk_i32 s2, 0x1000
	v_cmp_gt_i32_e32 vcc, s2, v4
	s_nop 1
	v_cndmask_b32_e32 v7, v6, v102, vcc
	v_and_b32_e32 v7, 1, v7
	v_cmp_eq_u32_e32 vcc, 1, v7
	s_nop 1
	v_cndmask_b32_e64 v7, v171, 0, vcc
	v_add_u32_e32 v7, v103, v7
	ds_read_b128 v[8:11], v86 offset:6528
	ds_read_b128 v[12:15], v7
	s_and_b64 vcc, exec, s[0:1]
	s_waitcnt vmcnt(7) lgkmcnt(0)
	v_pk_fma_f32 v[2:3], v[10:11], v[14:15], v[224:225]
	v_pk_fma_f32 v[0:1], v[8:9], v[12:13], v[222:223]
	global_store_dwordx4 v[16:17], v[0:3], off
	s_cbranch_vccnz .LBB0_1527
	ds_read_b128 v[8:11], v7 offset:2048
	v_lshlrev_b64 v[4:5], 10, v[4:5]
	v_lshl_add_u64 v[4:5], v[4:5], 1, s[50:51]
	v_lshl_add_u64 v[4:5], v[98:99], 1, v[4:5]
	s_waitcnt lgkmcnt(0)
	v_pk_mul_f32 v[8:9], v[0:1], v[8:9]
	v_pk_mul_f32 v[0:1], v[0:1], v[0:1]
	v_pk_mul_f32 v[10:11], v[2:3], v[10:11]
	v_pk_mul_f32 v[2:3], v[2:3], v[2:3]
	v_add_f32_e32 v0, v0, v1
	v_add_f32_e32 v0, v2, v0
	v_add_f32_e32 v0, v3, v0
	v_cvt_pk_bf16_f32 v8, v8, v9
	v_cvt_pk_bf16_f32 v9, v10, v11
	v_add_f32_dpp v0, v0, v0 quad_perm:[1,0,3,2] row_mask:0xf bank_mask:0xf bound_ctrl:1
	global_store_dwordx2 v[4:5], v[8:9], off
	s_nop 0
	v_add_f32_dpp v0, v0, v0 quad_perm:[2,3,0,1] row_mask:0xf bank_mask:0xf bound_ctrl:1
	s_nop 1
	v_add_f32_dpp v0, v0, v0 row_half_mirror row_mask:0xf bank_mask:0xf bound_ctrl:1
	s_nop 1
	v_mov_b32_dpp v1, v0 row_mirror row_mask:0xf bank_mask:0xf bound_ctrl:1
	s_and_saveexec_b64 s[2:3], s[36:37]
	s_cbranch_execz .LBB0_1526
	v_mov_b32_e32 v81, v129
	v_ashrrev_i32_e32 v97, 31, v96
	v_lshl_add_u64 v[2:3], s[54:55], 0, v[68:69]
	v_lshl_add_u64 v[4:5], v[96:97], 0, v[80:81]
	v_lshl_add_u64 v[2:3], v[4:5], 2, v[2:3]
	v_add_f32_e32 v0, v0, v1
	global_store_dword v[2:3], v0, off offset:256

.LBB0_1527:
	v_or_b32_e32 v4, v34, v82
	v_ashrrev_i32_e32 v5, 31, v4
	v_lshlrev_b64 v[0:1], 12, v[4:5]
	v_lshl_add_u64 v[0:1], s[40:41], 0, v[0:1]
	v_lshl_add_u64 v[16:17], v[98:99], 2, v[0:1]
	s_movk_i32 s2, 0x1000
	v_cmp_gt_i32_e32 vcc, s2, v4
	s_nop 1
	v_cndmask_b32_e32 v6, v6, v102, vcc
	v_and_b32_e32 v6, 1, v6
	v_cmp_eq_u32_e32 vcc, 1, v6
	s_nop 1
	v_cndmask_b32_e64 v6, v171, 0, vcc
	v_add_u32_e32 v6, v103, v6
	ds_read_b128 v[8:11], v86 offset:7616
	ds_read_b128 v[12:15], v6
	s_and_b64 vcc, exec, s[0:1]
	s_waitcnt vmcnt(7) lgkmcnt(0)
	v_pk_fma_f32 v[2:3], v[10:11], v[14:15], v[228:229]
	v_pk_fma_f32 v[0:1], v[8:9], v[12:13], v[226:227]
	global_store_dwordx4 v[16:17], v[0:3], off
	s_cbranch_vccnz .LBB0_1430
	ds_read_b128 v[6:9], v6 offset:2048
	v_lshlrev_b64 v[4:5], 10, v[4:5]
	v_lshl_add_u64 v[4:5], v[4:5], 1, s[50:51]
	v_lshl_add_u64 v[4:5], v[98:99], 1, v[4:5]
	s_waitcnt lgkmcnt(0)
	v_pk_mul_f32 v[6:7], v[0:1], v[6:7]
	v_pk_mul_f32 v[0:1], v[0:1], v[0:1]
	v_pk_mul_f32 v[8:9], v[2:3], v[8:9]
	v_pk_mul_f32 v[2:3], v[2:3], v[2:3]
	v_add_f32_e32 v0, v0, v1
	v_add_f32_e32 v0, v2, v0
	v_add_f32_e32 v0, v3, v0
	v_cvt_pk_bf16_f32 v6, v6, v7
	v_cvt_pk_bf16_f32 v7, v8, v9
	v_add_f32_dpp v0, v0, v0 quad_perm:[1,0,3,2] row_mask:0xf bank_mask:0xf bound_ctrl:1
	global_store_dwordx2 v[4:5], v[6:7], off
	s_nop 0
	v_add_f32_dpp v0, v0, v0 quad_perm:[2,3,0,1] row_mask:0xf bank_mask:0xf bound_ctrl:1
	s_nop 1
	v_add_f32_dpp v0, v0, v0 row_half_mirror row_mask:0xf bank_mask:0xf bound_ctrl:1
	s_nop 1
	v_mov_b32_dpp v1, v0 row_mirror row_mask:0xf bank_mask:0xf bound_ctrl:1
	s_and_saveexec_b64 s[0:1], s[36:37]
	s_cbranch_execz .LBB0_1429
	v_mov_b32_e32 v83, v129
	v_ashrrev_i32_e32 v97, 31, v96
	v_lshl_add_u64 v[2:3], s[54:55], 0, v[68:69]
	v_lshl_add_u64 v[4:5], v[96:97], 0, v[82:83]
	v_lshl_add_u64 v[2:3], v[4:5], 2, v[2:3]
	v_add_f32_e32 v0, v0, v1
	global_store_dword v[2:3], v0, off offset:256
	s_branch .LBB0_1429
